# phase 3: ssm conv loads and kv-path norm/rotary loads issued together instead of one round trip each
# speedup vs baseline: 1.1509x; 1.0032x over previous
; DI int get_tid() { int t = (int)__builtin_amdgcn_workitem_id_x(); asm volatile("" : "+v"(t)); return t; }
; DI int crow(int reg, int h) { return (reg & 3) + 8 * (reg >> 2) + 4 * h; }
; DI void row_info(int r, int& b, int& t, int& L) { if (r < NL) { b = r >> 12; t = r & 4095; L = SEQ; } else { int q = r - NL; b = q >> 8; t = q & 255; L = CTX; } }
; DI void qkv_item(const Params& p, int layer, int it, unsigned char* smem) {
;     const int tid = get_tid(), lane = tid & 63, wave = tid >> 6, li = lane & 31, lh = lane >> 5;
;     const int ug = it & 3, hd0 = 3 * (ug & 1);
;     const int rbase = (it >> 2) * 128 + 32 * wave;
;     const bf16_t* PROJ = (const bf16_t*)(p.ws + WS_PROJ);
;     bf16_t* Ws = (bf16_t*)smem;
;     int b, t0, L; row_info(rbase, b, t0, L);
;     const bool lat = rbase < NL;
;     float cs[16], sn[16];
;     {
;         const int axis = li >> 4, f = li & 7; const float inv = exp2f(-(float)f * (13.287712379549449f / 8.f));
; #pragma unroll
;         for (int reg = 0; reg < 16; ++reg) { int t = t0 + crow(reg, lh); float pos = (float)(axis ? (t & 63) : (t >> 6)); const float ang = pos * inv; cs[reg] = __cosf(ang); sn[reg] = __sinf(ang); }
;     }
;     const bool second = (li >> 3) & 1;
.LBB0_1248:
	s_and_b64 vcc, exec, s[0:1]
	s_cbranch_vccz .LBB0_1463
	v_mov_b32_e32 v1, v168
	s_lshl_b32 s1, s13, 5
	s_addk_i32 s1, 0x6f00
	v_ashrrev_i32_e32 v2, 1, v1
	s_and_b32 s1, s1, 0x7f80
	v_and_b32_e32 v4, 0xffffffe0, v2
	v_add_u32_e32 v7, s1, v4
	v_add_u32_e32 v4, 0xffffc000, v7
	s_and_b32 s0, 1, s13
	s_and_b32 s8, s13, 2
	v_lshrrev_b32_e32 v69, 8, v4
	v_and_b32_e32 v4, 7, v1
	s_cmp_eq_u32 s0, 1
	s_movk_i32 s0, 0x3fff
	v_cvt_f32_ubyte0_e32 v4, v4
	v_cmp_lt_i32_e64 s[36:37], s0, v7
	v_mul_f32_e32 v5, 0xbfd49a78, v4
	s_mov_b32 s0, 0xc2fc0000
	v_cmp_gt_f32_e32 vcc, s0, v5
	v_mov_b32_e32 v5, 0x42800000
	v_cmp_gt_i32_e64 s[38:39], s7, v7
	v_cndmask_b32_e32 v5, 0, v5, vcc
	v_fmac_f32_e32 v5, 0xbfd49a78, v4
	v_exp_f32_e32 v4, v5
	v_mov_b32_e32 v5, 0xe0
	v_mov_b32_e32 v6, 0xfe0
	v_bfe_u32 v151, v1, 5, 1
	v_cndmask_b32_e64 v5, v5, v6, s[38:39]
	v_and_b32_e32 v0, 31, v1
	v_and_b32_e32 v68, v5, v7
	v_cndmask_b32_e32 v5, 0, v183, vcc
	v_lshlrev_b32_e32 v72, 2, v151
	v_ldexp_f32 v4, v4, v5
	v_and_or_b32 v2, v2, 32, v72
	v_lshrrev_b32_e32 v5, 6, v68
	v_cmp_gt_u32_e32 vcc, 16, v0
	s_cselect_b32 s9, 3, 0
	v_ashrrev_i32_e32 v146, 12, v7
	v_cndmask_b32_e32 v6, v2, v5, vcc
	v_cvt_f32_ubyte0_e32 v6, v6
	v_mul_f32_e32 v6, v4, v6
	v_mul_f32_e32 v6, 0.15915494, v6
	v_cos_f32_e32 v73, v6
	v_sin_f32_e32 v75, v6
	v_or_b32_e32 v6, 1, v2
	v_cndmask_b32_e32 v6, v6, v5, vcc
	v_cvt_f32_ubyte0_e32 v6, v6
	v_mul_f32_e32 v6, v4, v6
	v_mul_f32_e32 v6, 0.15915494, v6
	v_cos_f32_e32 v77, v6
	v_sin_f32_e32 v87, v6
	v_or_b32_e32 v6, 2, v2
	v_cndmask_b32_e32 v6, v6, v5, vcc
	v_cvt_f32_ubyte0_e32 v6, v6
	v_mul_f32_e32 v6, v4, v6
	v_mul_f32_e32 v6, 0.15915494, v6
	v_cos_f32_e32 v118, v6
	v_sin_f32_e32 v119, v6
	v_or_b32_e32 v6, 3, v2
	v_cndmask_b32_e32 v6, v6, v5, vcc
	v_cvt_f32_ubyte0_e32 v6, v6
	v_mul_f32_e32 v6, v4, v6
	v_mul_f32_e32 v6, 0.15915494, v6
	v_cos_f32_e32 v120, v6
	v_sin_f32_e32 v121, v6
	v_or_b32_e32 v6, 8, v2
	v_cndmask_b32_e32 v6, v6, v5, vcc
	v_cvt_f32_ubyte0_e32 v6, v6
	v_mul_f32_e32 v6, v4, v6
	v_mul_f32_e32 v6, 0.15915494, v6
	v_cos_f32_e32 v122, v6
	v_sin_f32_e32 v123, v6
	v_or_b32_e32 v6, 9, v2
	v_cndmask_b32_e32 v6, v6, v5, vcc
	v_cvt_f32_ubyte0_e32 v6, v6
	v_mul_f32_e32 v6, v4, v6
	v_mul_f32_e32 v6, 0.15915494, v6
	v_cos_f32_e32 v124, v6
	v_sin_f32_e32 v125, v6
	v_or_b32_e32 v6, 10, v2
	v_cndmask_b32_e32 v6, v6, v5, vcc
	v_cvt_f32_ubyte0_e32 v6, v6
	v_mul_f32_e32 v6, v4, v6
	v_mul_f32_e32 v6, 0.15915494, v6
	v_cos_f32_e32 v126, v6
	v_sin_f32_e32 v127, v6
	v_or_b32_e32 v6, 11, v2
	v_cndmask_b32_e32 v6, v6, v5, vcc
	v_cvt_f32_ubyte0_e32 v6, v6
	v_mul_f32_e32 v6, v4, v6
	v_mul_f32_e32 v6, 0.15915494, v6
	v_cos_f32_e32 v128, v6
	v_sin_f32_e32 v129, v6
	v_or_b32_e32 v6, 16, v2
	v_cndmask_b32_e32 v6, v6, v5, vcc
	v_cvt_f32_ubyte0_e32 v6, v6
	v_mul_f32_e32 v6, v4, v6
	v_mul_f32_e32 v6, 0.15915494, v6
	v_cos_f32_e32 v130, v6
	v_sin_f32_e32 v131, v6
	v_or_b32_e32 v6, 17, v2
	v_cndmask_b32_e32 v6, v6, v5, vcc
	v_cvt_f32_ubyte0_e32 v6, v6
	v_mul_f32_e32 v6, v4, v6
	v_mul_f32_e32 v6, 0.15915494, v6
	v_cos_f32_e32 v132, v6
	v_sin_f32_e32 v133, v6
	v_or_b32_e32 v6, 18, v2
	v_cndmask_b32_e32 v6, v6, v5, vcc
	v_cvt_f32_ubyte0_e32 v6, v6
	v_mul_f32_e32 v6, v4, v6
	v_mul_f32_e32 v6, 0.15915494, v6
	v_cos_f32_e32 v134, v6
	v_sin_f32_e32 v135, v6
	v_or_b32_e32 v6, 19, v2
	v_cndmask_b32_e32 v6, v6, v5, vcc
	v_cvt_f32_ubyte0_e32 v6, v6
	v_mul_f32_e32 v6, v4, v6
	v_mul_f32_e32 v6, 0.15915494, v6
	v_cos_f32_e32 v136, v6
	v_sin_f32_e32 v137, v6
	v_or_b32_e32 v6, 24, v2
	v_cndmask_b32_e32 v6, v6, v5, vcc
	v_cvt_f32_ubyte0_e32 v6, v6
	v_mul_f32_e32 v6, v4, v6
	v_mul_f32_e32 v6, 0.15915494, v6
	v_cos_f32_e32 v138, v6
	v_sin_f32_e32 v139, v6
	v_or_b32_e32 v6, 25, v2
	v_cndmask_b32_e32 v6, v6, v5, vcc
	v_cvt_f32_ubyte0_e32 v6, v6
	v_mul_f32_e32 v6, v4, v6
	v_mul_f32_e32 v6, 0.15915494, v6
	v_cos_f32_e32 v140, v6
	v_sin_f32_e32 v141, v6
	v_or_b32_e32 v6, 26, v2
	v_or_b32_e32 v2, 27, v2
	v_cndmask_b32_e32 v6, v6, v5, vcc
	v_cndmask_b32_e32 v2, v2, v5, vcc
	v_cvt_f32_ubyte0_e32 v6, v6
	v_cvt_f32_ubyte0_e32 v2, v2
	v_mul_f32_e32 v6, v4, v6
	v_mul_f32_e32 v2, v4, v2
	v_mul_f32_e32 v6, 0.15915494, v6
	v_mul_f32_e32 v2, 0.15915494, v2
	v_cos_f32_e32 v142, v6
	v_sin_f32_e32 v143, v6
	v_cos_f32_e32 v144, v2
	v_sin_f32_e32 v145, v2
	v_and_b32_e32 v2, 8, v1
	v_cmp_ne_u32_e64 s[40:41], 0, v2
	s_mov_b64 s[0:1], -1
	s_cmp_lg_u32 s8, 0
	v_or_b32_e32 v152, v7, v0
	v_lshlrev_b32_e32 v78, 4, v151
	v_lshlrev_b32_e32 v148, 2, v0
	v_or_b32_e32 v76, 32, v0
	v_or_b32_e32 v74, 64, v0
	v_lshlrev_b32_e32 v147, 4, v1
	v_mul_u32_u24_e32 v70, 0x300, v151
	s_cbranch_scc0 .LBB0_1353
; DI float bf2f(bf16_t v) { return __uint_as_float(((unsigned)v) << 16); }
; DI void qkv_item(const Params& p, int layer, int it, unsigned char* smem) {
;     ...
;         const bf16_t* Wkv = (const bf16_t*)(p.ws + wbase(layer) + W_UKV);
;         const float* gk = p.in[I_GKH] + layer * 96;
;         const bf16_t* arow = PROJ + (size_t)(rbase + li) * INP + O_CKV + 8 * lh;
;         float ss = 0.f;
;         { bf16x8 a[8];
; #pragma unroll
;           for (int ks = 0; ks < 8; ++ks) a[ks] = ld8(arow + 16 * ks);
; #pragma unroll
;           for (int ks = 0; ks < 8; ++ks) {
; #pragma unroll
;             for (int j = 0; j < 8; ++j) { float x = bf2f((bf16_t)a[ks][j]); ss += x * x; } } }
	v_mov_b64_e32 v[4:5], s[2:3]
	v_mad_i64_i32 v[8:9], s[0:1], v152, s89, v[4:5]
	v_mov_b32_e32 v79, v3
	v_lshl_add_u64 v[80:81], v[8:9], 0, v[78:79]
	global_load_dwordx4 v[8:11], v[80:81], off offset:512
	global_load_dwordx4 v[154:157], v[80:81], off offset:544
	global_load_dwordx4 v[158:161], v[80:81], off offset:576
	global_load_dwordx4 v[162:165], v[80:81], off offset:608
	global_load_dwordx4 v[190:193], v[80:81], off offset:640
	global_load_dwordx4 v[194:197], v[80:81], off offset:672
	global_load_dwordx4 v[198:201], v[80:81], off offset:704
	v_cndmask_b32_e64 v6, v69, v146, s[38:39]
	v_mov_b32_e32 v173, 0x4000
	v_mov_b32_e32 v189, 0x3000
	v_mov_b32_e32 v188, 0x2000
	v_mul_lo_u32 v210, v6, 6
	v_mov_b32_e32 v83, v3
	v_mul_hi_u32_u24_e32 v89, 0x2200, v0
	v_mul_u32_u24_e32 v88, 0x2200, v0
	v_mul_hi_u32_u24_e32 v91, 0x2200, v76
	v_mul_u32_u24_e32 v90, 0x2200, v76
	v_mov_b32_e32 v71, v3
	v_mov_b32_e32 v93, v3
	v_mov_b32_e32 v95, v3
	v_mov_b32_e32 v97, v3
	v_mov_b32_e32 v99, v3
	v_mov_b32_e32 v101, v3
	v_mov_b32_e32 v103, v3
	s_add_i32 s8, s9, 2
	v_lshlrev_b32_e32 v106, 1, v76
	v_lshlrev_b32_e32 v108, 1, v74
	v_lshlrev_b32_e32 v110, 1, v72
	s_mov_b32 s42, s9
	s_waitcnt vmcnt(0)
	v_and_b32_e32 v2, 0xffff0000, v8
	v_lshlrev_b32_e32 v12, 16, v8
	v_mul_f32_e32 v2, v2, v2
	v_fmac_f32_e32 v2, v12, v12
	v_lshlrev_b32_e32 v8, 16, v9
	v_fmac_f32_e32 v2, v8, v8
	v_and_b32_e32 v8, 0xffff0000, v9
	v_fmac_f32_e32 v2, v8, v8
	v_lshlrev_b32_e32 v8, 16, v10
	v_fmac_f32_e32 v2, v8, v8
	v_and_b32_e32 v8, 0xffff0000, v10
	v_fmac_f32_e32 v2, v8, v8
	v_lshlrev_b32_e32 v8, 16, v11
	v_fmac_f32_e32 v2, v8, v8
	v_and_b32_e32 v8, 0xffff0000, v11
	v_fmac_f32_e32 v2, v8, v8
	s_nop 0
	s_waitcnt vmcnt(0)
	v_lshlrev_b32_e32 v12, 16, v154
	v_fmac_f32_e32 v2, v12, v12
	v_and_b32_e32 v154, 0xffff0000, v154
	v_fmac_f32_e32 v2, v154, v154
	v_lshlrev_b32_e32 v154, 16, v155
	v_fmac_f32_e32 v2, v154, v154
	v_and_b32_e32 v154, 0xffff0000, v155
	v_fmac_f32_e32 v2, v154, v154
	v_lshlrev_b32_e32 v154, 16, v156
	v_fmac_f32_e32 v2, v154, v154
	v_and_b32_e32 v154, 0xffff0000, v156
	v_fmac_f32_e32 v2, v154, v154
	v_lshlrev_b32_e32 v154, 16, v157
	v_fmac_f32_e32 v2, v154, v154
	v_and_b32_e32 v154, 0xffff0000, v157
	v_fmac_f32_e32 v2, v154, v154
	s_nop 0
	s_waitcnt vmcnt(0)
	v_lshlrev_b32_e32 v12, 16, v158
	v_fmac_f32_e32 v2, v12, v12
	v_and_b32_e32 v158, 0xffff0000, v158
	v_fmac_f32_e32 v2, v158, v158
	v_lshlrev_b32_e32 v158, 16, v159
	v_fmac_f32_e32 v2, v158, v158
	v_and_b32_e32 v158, 0xffff0000, v159
	v_fmac_f32_e32 v2, v158, v158
	v_lshlrev_b32_e32 v158, 16, v160
	v_fmac_f32_e32 v2, v158, v158
	v_and_b32_e32 v158, 0xffff0000, v160
	v_fmac_f32_e32 v2, v158, v158
	v_lshlrev_b32_e32 v158, 16, v161
	v_fmac_f32_e32 v2, v158, v158
	v_and_b32_e32 v158, 0xffff0000, v161
	v_fmac_f32_e32 v2, v158, v158
	s_nop 0
	s_waitcnt vmcnt(0)
	v_lshlrev_b32_e32 v12, 16, v162
	v_fmac_f32_e32 v2, v12, v12
	v_and_b32_e32 v162, 0xffff0000, v162
	v_fmac_f32_e32 v2, v162, v162
	v_lshlrev_b32_e32 v162, 16, v163
	v_fmac_f32_e32 v2, v162, v162
	v_and_b32_e32 v162, 0xffff0000, v163
	v_fmac_f32_e32 v2, v162, v162
	v_lshlrev_b32_e32 v162, 16, v164
	v_fmac_f32_e32 v2, v162, v162
	v_and_b32_e32 v162, 0xffff0000, v164
	v_fmac_f32_e32 v2, v162, v162
	v_lshlrev_b32_e32 v162, 16, v165
	v_fmac_f32_e32 v2, v162, v162
	v_and_b32_e32 v162, 0xffff0000, v165
	v_fmac_f32_e32 v2, v162, v162
	s_nop 0
	s_waitcnt vmcnt(0)
	v_lshlrev_b32_e32 v12, 16, v190
	v_fmac_f32_e32 v2, v12, v12
	v_and_b32_e32 v190, 0xffff0000, v190
	v_fmac_f32_e32 v2, v190, v190
	v_lshlrev_b32_e32 v190, 16, v191
	v_fmac_f32_e32 v2, v190, v190
	v_and_b32_e32 v190, 0xffff0000, v191
	v_fmac_f32_e32 v2, v190, v190
	v_lshlrev_b32_e32 v190, 16, v192
	v_fmac_f32_e32 v2, v190, v190
	v_and_b32_e32 v190, 0xffff0000, v192
	v_fmac_f32_e32 v2, v190, v190
	v_lshlrev_b32_e32 v190, 16, v193
	v_fmac_f32_e32 v2, v190, v190
	v_and_b32_e32 v190, 0xffff0000, v193
	v_fmac_f32_e32 v2, v190, v190
	s_nop 0
	s_waitcnt vmcnt(0)
	v_lshlrev_b32_e32 v12, 16, v194
	v_fmac_f32_e32 v2, v12, v12
	v_and_b32_e32 v194, 0xffff0000, v194
	v_fmac_f32_e32 v2, v194, v194
	v_lshlrev_b32_e32 v194, 16, v195
	v_fmac_f32_e32 v2, v194, v194
	v_and_b32_e32 v194, 0xffff0000, v195
	v_fmac_f32_e32 v2, v194, v194
	v_lshlrev_b32_e32 v194, 16, v196
	v_fmac_f32_e32 v2, v194, v194
	v_and_b32_e32 v194, 0xffff0000, v196
	v_fmac_f32_e32 v2, v194, v194
	v_lshlrev_b32_e32 v194, 16, v197
	v_fmac_f32_e32 v2, v194, v194
	v_and_b32_e32 v194, 0xffff0000, v197
	v_fmac_f32_e32 v2, v194, v194
	s_nop 0
	s_waitcnt vmcnt(0)
	v_lshlrev_b32_e32 v12, 16, v198
	v_fmac_f32_e32 v2, v12, v12
	v_and_b32_e32 v198, 0xffff0000, v198
	v_fmac_f32_e32 v2, v198, v198
	v_lshlrev_b32_e32 v198, 16, v199
	v_fmac_f32_e32 v2, v198, v198
	v_and_b32_e32 v198, 0xffff0000, v199
	v_fmac_f32_e32 v2, v198, v198
	v_lshlrev_b32_e32 v198, 16, v200
	v_fmac_f32_e32 v2, v198, v198
	v_and_b32_e32 v198, 0xffff0000, v200
	v_fmac_f32_e32 v2, v198, v198
	v_lshlrev_b32_e32 v198, 16, v201
	v_fmac_f32_e32 v2, v198, v198
	v_and_b32_e32 v198, 0xffff0000, v201
	v_fmac_f32_e32 v2, v198, v198
	global_load_dwordx4 v[8:11], v[80:81], off offset:736
	s_waitcnt vmcnt(0)
	v_lshlrev_b32_e32 v12, 16, v8
	v_fmac_f32_e32 v2, v12, v12
	v_and_b32_e32 v8, 0xffff0000, v8
	v_fmac_f32_e32 v2, v8, v8
	v_lshlrev_b32_e32 v8, 16, v9
	v_fmac_f32_e32 v2, v8, v8
	v_and_b32_e32 v8, 0xffff0000, v9
	v_fmac_f32_e32 v2, v8, v8
	v_lshlrev_b32_e32 v8, 16, v10
	v_fmac_f32_e32 v2, v8, v8
	v_and_b32_e32 v8, 0xffff0000, v10
	v_fmac_f32_e32 v2, v8, v8
	v_lshlrev_b32_e32 v8, 16, v11
	v_fmac_f32_e32 v2, v8, v8
	v_and_b32_e32 v8, 0xffff0000, v11
	v_and_b32_e32 v9, 64, v182
	v_fmac_f32_e32 v2, v8, v8
	v_xor_b32_e32 v10, 32, v182
	v_add_u32_e32 v8, 64, v9
	v_cmp_lt_i32_e32 vcc, v10, v8
	s_nop 1
	v_cndmask_b32_e32 v10, v182, v10, vcc
	v_lshlrev_b32_e32 v10, 2, v10
	ds_bpermute_b32 v10, v10, v2
	s_waitcnt lgkmcnt(0)
; DI float bf2f(bf16_t v) { return __uint_as_float(((unsigned)v) << 16); }
; DI int crow(int reg, int h) { return (reg & 3) + 8 * (reg >> 2) + 4 * h; }
; DI void qkv_item(const Params& p, int layer, int it, unsigned char* smem) {
;     ...
;         ss += __shfl_xor(ss, 32);
;         const float alpha = 1.f / sqrtf(ss * (1.f / 128.f) + EPS);
;         float al[16], krv[16];
; #pragma unroll
;         for (int reg = 0; reg < 16; ++reg) { al[reg] = __shfl(alpha, crow(reg, lh)); krv[reg] = bf2f(PROJ[(size_t)(rbase + crow(reg, lh)) * INP + O_KR + li]); }
;         const float g0 = gk[li], g1 = gk[32 + li], g2 = gk[64 + li];
	v_add_f32_e32 v2, v2, v10
	v_fmamk_f32 v2, v2, 0x3c000000, v169
	v_cmp_gt_f32_e32 vcc, s28, v2
	v_mul_f32_e32 v10, 0x4f800000, v2
	s_nop 0
	v_cndmask_b32_e32 v2, v2, v10, vcc
	v_sqrt_f32_e32 v10, v2
	s_nop 0
	v_add_u32_e32 v11, -1, v10
	v_fma_f32 v12, -v11, v10, v2
	v_cmp_ge_f32_e64 s[0:1], 0, v12
	v_add_u32_e32 v12, 1, v10
	s_nop 0
	v_cndmask_b32_e64 v11, v10, v11, s[0:1]
	v_fma_f32 v10, -v12, v10, v2
	v_cmp_lt_f32_e64 s[0:1], 0, v10
	s_nop 1
	v_cndmask_b32_e64 v10, v11, v12, s[0:1]
	v_mul_f32_e32 v11, 0x37800000, v10
	v_cndmask_b32_e32 v10, v10, v11, vcc
	v_cmp_class_f32_e32 vcc, v2, v170
	s_nop 1
	v_cndmask_b32_e32 v2, v10, v2, vcc
	v_div_scale_f32 v10, s[0:1], v2, v2, 1.0
	v_rcp_f32_e32 v11, v10
	s_nop 0
	v_fma_f32 v12, -v10, v11, 1.0
	v_fmac_f32_e32 v11, v12, v11
	v_div_scale_f32 v12, vcc, 1.0, v2, 1.0
	v_mul_f32_e32 v13, v12, v11
	v_fma_f32 v14, -v10, v13, v12
	v_fmac_f32_e32 v13, v14, v11
	v_fma_f32 v10, -v10, v13, v12
	v_div_fmas_f32 v10, v10, v11, v13
	v_div_fixup_f32 v11, v10, v2, 1.0
	v_or_b32_e32 v2, v9, v72
	v_lshlrev_b32_e32 v2, 2, v2
	ds_bpermute_b32 v79, v2, v11
	v_lshlrev_b32_e32 v2, 1, v0
	v_or_b32_e32 v202, v72, v7
	v_mad_i64_i32 v[204:205], s[0:1], v202, s89, v[4:5]
	v_lshl_add_u64 v[204:205], v[204:205], 0, v[2:3]
	global_load_ushort v153, v[204:205], off offset:768
	v_or_b32_e32 v202, 1, v72
	v_or_b32_e32 v202, v202, v7
	v_mad_i64_i32 v[204:205], s[0:1], v202, s89, v[4:5]
	v_lshl_add_u64 v[204:205], v[204:205], 0, v[2:3]
	global_load_ushort v155, v[204:205], off offset:768
	v_or_b32_e32 v202, 2, v72
	v_or_b32_e32 v202, v202, v7
	v_mad_i64_i32 v[204:205], s[0:1], v202, s89, v[4:5]
	v_lshl_add_u64 v[204:205], v[204:205], 0, v[2:3]
	global_load_ushort v157, v[204:205], off offset:768
	v_or_b32_e32 v202, 3, v72
	v_or_b32_e32 v202, v202, v7
	v_mad_i64_i32 v[204:205], s[0:1], v202, s89, v[4:5]
	v_lshl_add_u64 v[204:205], v[204:205], 0, v[2:3]
	global_load_ushort v159, v[204:205], off offset:768
	v_or_b32_e32 v202, 8, v72
	v_or_b32_e32 v202, v202, v7
	v_mad_i64_i32 v[204:205], s[0:1], v202, s89, v[4:5]
	v_lshl_add_u64 v[204:205], v[204:205], 0, v[2:3]
	global_load_ushort v161, v[204:205], off offset:768
	v_or_b32_e32 v202, 9, v72
	v_or_b32_e32 v202, v202, v7
	v_mad_i64_i32 v[204:205], s[0:1], v202, s89, v[4:5]
	v_lshl_add_u64 v[204:205], v[204:205], 0, v[2:3]
	global_load_ushort v163, v[204:205], off offset:768
	v_or_b32_e32 v202, 10, v72
	v_or_b32_e32 v202, v202, v7
	v_mad_i64_i32 v[204:205], s[0:1], v202, s89, v[4:5]
	v_lshl_add_u64 v[204:205], v[204:205], 0, v[2:3]
	global_load_ushort v165, v[204:205], off offset:768
	v_or_b32_e32 v202, 11, v72
	v_or_b32_e32 v202, v202, v7
	v_mad_i64_i32 v[204:205], s[0:1], v202, s89, v[4:5]
	v_lshl_add_u64 v[204:205], v[204:205], 0, v[2:3]
	global_load_ushort v167, v[204:205], off offset:768
	v_or_b32_e32 v202, 16, v72
	v_or_b32_e32 v202, v202, v7
	v_mad_i64_i32 v[204:205], s[0:1], v202, s89, v[4:5]
	v_lshl_add_u64 v[204:205], v[204:205], 0, v[2:3]
	global_load_ushort v191, v[204:205], off offset:768
	v_or_b32_e32 v202, 17, v72
	v_or_b32_e32 v202, v202, v7
	v_mad_i64_i32 v[204:205], s[0:1], v202, s89, v[4:5]
	v_lshl_add_u64 v[204:205], v[204:205], 0, v[2:3]
	global_load_ushort v193, v[204:205], off offset:768
	v_or_b32_e32 v202, 18, v72
	v_or_b32_e32 v202, v202, v7
	v_mad_i64_i32 v[204:205], s[0:1], v202, s89, v[4:5]
	v_lshl_add_u64 v[204:205], v[204:205], 0, v[2:3]
	global_load_ushort v195, v[204:205], off offset:768
	v_or_b32_e32 v202, 19, v72
	v_or_b32_e32 v202, v202, v7
	v_mad_i64_i32 v[204:205], s[0:1], v202, s89, v[4:5]
	v_lshl_add_u64 v[204:205], v[204:205], 0, v[2:3]
	global_load_ushort v197, v[204:205], off offset:768
	v_or_b32_e32 v202, 24, v72
	v_or_b32_e32 v202, v202, v7
	v_mad_i64_i32 v[204:205], s[0:1], v202, s89, v[4:5]
	v_lshl_add_u64 v[204:205], v[204:205], 0, v[2:3]
	global_load_ushort v199, v[204:205], off offset:768
	v_or_b32_e32 v202, 25, v72
	v_or_b32_e32 v202, v202, v7
	v_mad_i64_i32 v[204:205], s[0:1], v202, s89, v[4:5]
	v_lshl_add_u64 v[204:205], v[204:205], 0, v[2:3]
	global_load_ushort v201, v[204:205], off offset:768
	v_or_b32_e32 v202, 26, v72
	v_or_b32_e32 v202, v202, v7
	v_mad_i64_i32 v[204:205], s[0:1], v202, s89, v[4:5]
	v_lshl_add_u64 v[204:205], v[204:205], 0, v[2:3]
	global_load_ushort v203, v[204:205], off offset:768
	v_or_b32_e32 v202, 27, v72
	v_or_b32_e32 v202, v202, v7
	v_mad_i64_i32 v[204:205], s[0:1], v202, s89, v[4:5]
	v_lshl_add_u64 v[204:205], v[204:205], 0, v[2:3]
	global_load_ushort v205, v[204:205], off offset:768
	v_or_b32_e32 v2, v72, v7
	v_mad_i64_i32 v[12:13], s[0:1], v2, s89, v[4:5]
	v_lshlrev_b32_e32 v2, 1, v0
	v_lshl_add_u64 v[12:13], v[12:13], 0, v[2:3]
	s_nop 0
	s_waitcnt vmcnt(0)
	v_lshlrev_b32_e32 v153, 16, v153
	v_or_b32_e32 v10, 1, v72
	v_or_b32_e32 v12, v9, v10
	v_lshlrev_b32_e32 v12, 2, v12
	ds_bpermute_b32 v154, v12, v11
	v_or_b32_e32 v12, v10, v7
	v_mad_i64_i32 v[12:13], s[0:1], v12, s89, v[4:5]
	v_lshl_add_u64 v[12:13], v[12:13], 0, v[2:3]
	s_nop 0
	v_mul_u32_u24_e32 v92, 0xc0, v10
	s_waitcnt vmcnt(0)
	v_lshlrev_b32_e32 v155, 16, v155
	v_or_b32_e32 v12, 2, v72
	v_or_b32_e32 v13, v9, v12
	v_lshlrev_b32_e32 v13, 2, v13
	v_or_b32_e32 v12, v12, v7
	ds_bpermute_b32 v156, v13, v11
	v_mad_i64_i32 v[12:13], s[0:1], v12, s89, v[4:5]
	v_lshl_add_u64 v[12:13], v[12:13], 0, v[2:3]
	s_nop 0
	s_waitcnt lgkmcnt(0)
	v_mul_f32_e32 v216, v156, v156
	s_waitcnt vmcnt(0)
	v_lshlrev_b32_e32 v157, 16, v157
	v_or_b32_e32 v12, 3, v72
	v_or_b32_e32 v13, v9, v12
	v_lshlrev_b32_e32 v13, 2, v13
	v_or_b32_e32 v12, v12, v7
	ds_bpermute_b32 v158, v13, v11
	v_mad_i64_i32 v[12:13], s[0:1], v12, s89, v[4:5]
	v_lshl_add_u64 v[12:13], v[12:13], 0, v[2:3]
	s_nop 0
	v_mul_f32_e32 v217, v157, v157
	s_waitcnt lgkmcnt(0)
; DI float bf2f(bf16_t v) { return __uint_as_float(((unsigned)v) << 16); }
; DI int crow(int reg, int h) { return (reg & 3) + 8 * (reg >> 2) + 4 * h; }
; DI float xor_red32(float v) { v += __shfl_xor(v, 16); v += __shfl_xor(v, 8); v += __shfl_xor(v, 4); v += __shfl_xor(v, 2); v += __shfl_xor(v, 1); return v; }
; DI void qkv_item(const Params& p, int layer, int it, unsigned char* smem) {
;     ...
;         for (int reg = 0; reg < 16; ++reg) { al[reg] = __shfl(alpha, crow(reg, lh)); krv[reg] = bf2f(PROJ[(size_t)(rbase + crow(reg, lh)) * INP + O_KR + li]); }
;         const float g0 = gk[li], g1 = gk[32 + li], g2 = gk[64 + li];
;         const int kbase = lat ? (CTX + t0) : t0;
	v_mul_f32_e32 v218, v158, v158
	s_waitcnt vmcnt(0)
	v_lshlrev_b32_e32 v159, 16, v159
	v_or_b32_e32 v12, 8, v72
	v_or_b32_e32 v13, v9, v12
	v_lshlrev_b32_e32 v13, 2, v13
	v_or_b32_e32 v12, v12, v7
	ds_bpermute_b32 v160, v13, v11
	v_mad_i64_i32 v[12:13], s[0:1], v12, s89, v[4:5]
	v_lshl_add_u64 v[12:13], v[12:13], 0, v[2:3]
	s_nop 0
	v_mul_f32_e32 v219, v159, v159
	s_waitcnt lgkmcnt(0)
	v_mul_f32_e32 v220, v160, v160
	s_waitcnt vmcnt(0)
	v_lshlrev_b32_e32 v161, 16, v161
	v_or_b32_e32 v12, 9, v72
	v_or_b32_e32 v13, v9, v12
	v_lshlrev_b32_e32 v13, 2, v13
	v_or_b32_e32 v12, v12, v7
	ds_bpermute_b32 v162, v13, v11
	v_mad_i64_i32 v[12:13], s[0:1], v12, s89, v[4:5]
	v_lshl_add_u64 v[12:13], v[12:13], 0, v[2:3]
	s_nop 0
	v_mul_f32_e32 v221, v161, v161
	s_waitcnt lgkmcnt(0)
	v_mul_f32_e32 v222, v162, v162
	s_waitcnt vmcnt(0)
	v_lshlrev_b32_e32 v163, 16, v163
	v_or_b32_e32 v12, 10, v72
	v_or_b32_e32 v13, v9, v12
	v_lshlrev_b32_e32 v13, 2, v13
	v_or_b32_e32 v12, v12, v7
	ds_bpermute_b32 v164, v13, v11
	v_mad_i64_i32 v[12:13], s[0:1], v12, s89, v[4:5]
	v_lshl_add_u64 v[12:13], v[12:13], 0, v[2:3]
	s_nop 0
	v_mul_f32_e32 v223, v163, v163
	s_waitcnt lgkmcnt(0)
	v_mul_f32_e32 v224, v164, v164
	s_waitcnt vmcnt(0)
	v_lshlrev_b32_e32 v165, 16, v165
	v_or_b32_e32 v12, 11, v72
	v_or_b32_e32 v13, v9, v12
	v_lshlrev_b32_e32 v13, 2, v13
	v_or_b32_e32 v12, v12, v7
	ds_bpermute_b32 v166, v13, v11
	v_mad_i64_i32 v[12:13], s[0:1], v12, s89, v[4:5]
	v_lshl_add_u64 v[12:13], v[12:13], 0, v[2:3]
	s_nop 0
	v_mul_f32_e32 v225, v165, v165
	s_waitcnt lgkmcnt(0)
	v_mul_f32_e32 v226, v166, v166
	s_waitcnt vmcnt(0)
	v_lshlrev_b32_e32 v167, 16, v167
	v_or_b32_e32 v12, 16, v72
	v_or_b32_e32 v13, v9, v12
	v_lshlrev_b32_e32 v13, 2, v13
	v_or_b32_e32 v12, v12, v7
	ds_bpermute_b32 v190, v13, v11
	v_mad_i64_i32 v[12:13], s[0:1], v12, s89, v[4:5]
	v_lshl_add_u64 v[12:13], v[12:13], 0, v[2:3]
	s_nop 0
	v_mul_f32_e32 v227, v167, v167
	s_waitcnt lgkmcnt(0)
	v_mul_f32_e32 v228, v190, v190
	s_waitcnt vmcnt(0)
	v_lshlrev_b32_e32 v191, 16, v191
	v_or_b32_e32 v12, 17, v72
	v_or_b32_e32 v13, v9, v12
	v_lshlrev_b32_e32 v13, 2, v13
	v_or_b32_e32 v12, v12, v7
	ds_bpermute_b32 v192, v13, v11
	v_mad_i64_i32 v[12:13], s[0:1], v12, s89, v[4:5]
	v_lshl_add_u64 v[12:13], v[12:13], 0, v[2:3]
	s_nop 0
	v_mul_f32_e32 v229, v191, v191
	s_waitcnt lgkmcnt(0)
	v_mul_f32_e32 v230, v192, v192
	s_waitcnt vmcnt(0)
	v_lshlrev_b32_e32 v193, 16, v193
	v_or_b32_e32 v12, 18, v72
	v_or_b32_e32 v13, v9, v12
	v_lshlrev_b32_e32 v13, 2, v13
	v_or_b32_e32 v12, v12, v7
	ds_bpermute_b32 v194, v13, v11
	v_mad_i64_i32 v[12:13], s[0:1], v12, s89, v[4:5]
	v_lshl_add_u64 v[12:13], v[12:13], 0, v[2:3]
	s_nop 0
	v_mul_f32_e32 v231, v193, v193
	s_waitcnt lgkmcnt(0)
	v_mul_f32_e32 v232, v194, v194
	s_waitcnt vmcnt(0)
	v_lshlrev_b32_e32 v195, 16, v195
	v_or_b32_e32 v12, 19, v72
	v_or_b32_e32 v13, v9, v12
	v_lshlrev_b32_e32 v13, 2, v13
	v_or_b32_e32 v12, v12, v7
	ds_bpermute_b32 v196, v13, v11
	v_mad_i64_i32 v[12:13], s[0:1], v12, s89, v[4:5]
	v_lshl_add_u64 v[12:13], v[12:13], 0, v[2:3]
	s_nop 0
	v_mul_f32_e32 v233, v195, v195
	s_waitcnt lgkmcnt(0)
	v_mul_f32_e32 v234, v196, v196
	s_waitcnt vmcnt(0)
	v_lshlrev_b32_e32 v197, 16, v197
	v_or_b32_e32 v12, 24, v72
	v_or_b32_e32 v13, v9, v12
	v_lshlrev_b32_e32 v13, 2, v13
	v_or_b32_e32 v12, v12, v7
	ds_bpermute_b32 v198, v13, v11
	v_mad_i64_i32 v[12:13], s[0:1], v12, s89, v[4:5]
	v_lshl_add_u64 v[12:13], v[12:13], 0, v[2:3]
	s_nop 0
	v_mul_f32_e32 v235, v197, v197
	s_waitcnt lgkmcnt(0)
	v_mul_f32_e32 v236, v198, v198
	s_waitcnt vmcnt(0)
	v_lshlrev_b32_e32 v199, 16, v199
	v_or_b32_e32 v12, 25, v72
	v_or_b32_e32 v13, v9, v12
	v_lshlrev_b32_e32 v13, 2, v13
	v_or_b32_e32 v12, v12, v7
	ds_bpermute_b32 v200, v13, v11
	v_mad_i64_i32 v[12:13], s[0:1], v12, s89, v[4:5]
	v_lshl_add_u64 v[12:13], v[12:13], 0, v[2:3]
	s_nop 0
	v_mul_f32_e32 v237, v199, v199
	s_waitcnt lgkmcnt(0)
	v_mul_f32_e32 v238, v200, v200
	s_waitcnt vmcnt(0)
	v_lshlrev_b32_e32 v201, 16, v201
	v_or_b32_e32 v12, 26, v72
	v_or_b32_e32 v13, v9, v12
	v_lshlrev_b32_e32 v13, 2, v13
	v_or_b32_e32 v12, v12, v7
	ds_bpermute_b32 v202, v13, v11
	v_mad_i64_i32 v[12:13], s[0:1], v12, s89, v[4:5]
	v_lshl_add_u64 v[12:13], v[12:13], 0, v[2:3]
	s_nop 0
	v_mul_f32_e32 v239, v201, v201
	s_waitcnt lgkmcnt(0)
	v_mul_f32_e32 v240, v202, v202
	s_waitcnt vmcnt(0)
	v_lshlrev_b32_e32 v203, 16, v203
	v_or_b32_e32 v12, 27, v72
	v_or_b32_e32 v7, v12, v7
	v_mad_i64_i32 v[4:5], s[0:1], v7, s89, v[4:5]
	v_lshl_add_u64 v[4:5], v[4:5], 0, v[2:3]
	s_nop 0
	v_readlane_b32 s0, v255, 36
	v_readlane_b32 s1, v255, 37
	s_nop 4
	global_load_dword v206, v148, s[0:1]
	global_load_dword v207, v148, s[0:1] offset:128
	global_load_dword v208, v148, s[0:1] offset:256
	v_readlane_b32 s0, v255, 34
	v_readlane_b32 s1, v255, 35
	v_or_b32_e32 v9, v9, v12
	v_lshlrev_b32_e32 v9, 2, v9
	ds_bpermute_b32 v204, v9, v11
	v_mul_f32_e32 v241, v203, v203
	s_waitcnt lgkmcnt(0)
	v_mul_f32_e32 v242, v204, v204
	s_waitcnt vmcnt(3)
	v_lshlrev_b32_e32 v205, 16, v205
	v_add_u32_e32 v2, 0x100, v68
	v_cndmask_b32_e64 v82, v68, v2, s[38:39]
	v_and_b32_e32 v2, 0xf0, v147
	v_lshl_add_u64 v[84:85], s[0:1], 0, v[2:3]
	v_add_u32_e32 v86, 0, v2
	v_mul_u32_u24_e32 v2, 0x110, v0
	v_add3_u32 v209, 0, v2, v78
	v_xor_b32_e32 v2, 16, v182
	v_cmp_lt_i32_e32 vcc, v2, v8
	s_movk_i32 s0, 0xc0
	v_mad_u32_u24 v94, v10, s0, s0
	v_cndmask_b32_e32 v2, v182, v2, vcc
	v_lshlrev_b32_e32 v211, 2, v2
	v_xor_b32_e32 v2, 8, v182
	v_cmp_lt_i32_e32 vcc, v2, v8
	v_mul_f32_e32 v243, v205, v205
	s_nop 0
	v_cndmask_b32_e32 v2, v182, v2, vcc
	v_lshlrev_b32_e32 v212, 2, v2
	v_xor_b32_e32 v2, 4, v182
	v_cmp_lt_i32_e32 vcc, v2, v8
	s_nop 1
	v_cndmask_b32_e32 v2, v182, v2, vcc
	v_lshlrev_b32_e32 v213, 2, v2
	v_xor_b32_e32 v2, 2, v182
	v_cmp_lt_i32_e32 vcc, v2, v8
	s_nop 1
	v_cndmask_b32_e32 v2, v182, v2, vcc
	v_lshlrev_b32_e32 v214, 2, v2
	v_xor_b32_e32 v2, 1, v182
	v_cmp_lt_i32_e32 vcc, v2, v8
	s_nop 1
	v_cndmask_b32_e32 v2, v182, v2, vcc
	v_lshlrev_b32_e32 v215, 2, v2
	v_mov_b32_e32 v2, 0x180
	v_mad_u32_u24 v96, v10, s0, v2
	v_mov_b32_e32 v2, 0x540
	v_mad_u32_u24 v98, v10, s0, v2
	v_mov_b32_e32 v2, 0xb40
	v_mad_u32_u24 v100, v10, s0, v2
	v_mov_b32_e32 v2, 0x1140
	v_mad_u32_u24 v102, v10, s0, v2
	v_readlane_b32 s0, v253, 30
	v_lshlrev_b32_e32 v2, 1, v82
	v_readlane_b32 s1, v253, 31
	s_nop 1
	v_lshl_add_u64 v[104:105], s[0:1], 0, v[2:3]
	s_branch .LBB0_1253

; DI float bf2f(bf16_t v) { return __uint_as_float(((unsigned)v) << 16); }
; DI float silu(float x) { return x / (1.f + __expf(-x)); }
; DI void ssmconv_item(const Params& p, int layer, int it, const float* w, const float* bb) {
;     ...
;         for (int j = 0; j < 5; ++j) { const int i = tid + 256 * (j0 + j), rl = i / 80, c = (i - rl * 80) * 8, t = t0 + rl; const size_t r = r0 + rl;
;             const bf16_t* src = PROJ + r * INP + O_XBC + c;
;             xc[j] = ld8(src); xp[j] = xc[j]; xn[j] = xc[j];
;             if (t > 0) xp[j] = ld8(src - INP);
;             if (t < L - 1) xn[j] = ld8(src + INP); }
; #pragma unroll
;         for (int j = 0; j < 5; ++j) { const int i = tid + 256 * (j0 + j), rl = i / 80, c = (i - rl * 80) * 8, t = t0 + rl; const size_t r = r0 + rl;
;             const bool hp = t > 0, hn = t < L - 1;
;             const f32x4 b0 = *(const f32x4*)(bb + c), b1 = *(const f32x4*)(bb + c + 4), wa0 = *(const f32x4*)(w + c), wa1 = *(const f32x4*)(w + c + 4),
;                         wb0 = *(const f32x4*)(w + 640 + c), wb1 = *(const f32x4*)(w + 640 + c + 4), wc0 = *(const f32x4*)(w + 1280 + c), wc1 = *(const f32x4*)(w + 1280 + c + 4);
;             const float bv[8] = { b0.x, b0.y, b0.z, b0.w, b1.x, b1.y, b1.z, b1.w }, w0v[8] = { wa0.x, wa0.y, wa0.z, wa0.w, wa1.x, wa1.y, wa1.z, wa1.w },
;                         w1v[8] = { wb0.x, wb0.y, wb0.z, wb0.w, wb1.x, wb1.y, wb1.z, wb1.w }, w2v[8] = { wc0.x, wc0.y, wc0.z, wc0.w, wc1.x, wc1.y, wc1.z, wc1.w };
;             float o[8];
; #pragma unroll
;             for (int e = 0; e < 8; ++e) { float v = bv[e] + w1v[e] * bf2f((bf16_t)xc[j][e]);
;                 if (hp) v += w0v[e] * bf2f((bf16_t)xp[j][e]);
;                 if (hn) v += w2v[e] * bf2f((bf16_t)xn[j][e]);
;                 o[e] = silu(v); }
;             *(bf16x8*)(UZ + r * 1024 + c) = pack8(o[0], o[1], o[2], o[3], o[4], o[5], o[6], o[7]); }
.LBB0_1508:
	s_or_b64 exec, exec, s[10:11]
	s_waitcnt vmcnt(0)
	v_mad_u64_u32 v[76:77], s[10:11], v66, s79, v[2:3]
	ds_read_b128 v[106:109], v76 offset:7680
	ds_read_b128 v[64:67], v76 offset:7696
	ds_read_b128 v[110:113], v76
	ds_read_b128 v[68:71], v76 offset:16
	ds_read_b128 v[114:117], v76 offset:2560
	ds_read_b128 v[72:75], v76 offset:2576
	ds_read_b128 v[118:121], v76 offset:5120
	ds_read_b128 v[76:79], v76 offset:5136
	v_lshlrev_b32_e32 v105, 16, v52
	s_waitcnt lgkmcnt(3)
	v_fma_f32 v105, v114, v105, v106
	v_lshlrev_b32_e32 v106, 16, v56
	v_fma_f32 v106, v110, v106, v105
	v_cndmask_b32_e64 v105, v105, v106, s[0:1]
	v_lshlrev_b32_e32 v106, 16, v60
	s_waitcnt lgkmcnt(1)
	v_fma_f32 v106, v118, v106, v105
	v_cndmask_b32_e64 v105, v105, v106, s[54:55]
	v_mul_f32_e32 v106, 0xbfb8aa3b, v105
	v_exp_f32_e32 v106, v106
	v_and_b32_e32 v52, 0xffff0000, v52
	v_fma_f32 v52, v115, v52, v107
	v_and_b32_e32 v56, 0xffff0000, v56
	v_add_f32_e32 v106, 1.0, v106
	v_div_scale_f32 v110, s[10:11], v106, v106, v105
	v_rcp_f32_e32 v114, v110
	v_fma_f32 v56, v111, v56, v52
	v_cndmask_b32_e64 v52, v52, v56, s[0:1]
	v_and_b32_e32 v56, 0xffff0000, v60
	v_fma_f32 v56, v119, v56, v52
	v_cndmask_b32_e64 v52, v52, v56, s[54:55]
	v_fma_f32 v118, -v110, v114, 1.0
	v_mul_f32_e32 v56, 0xbfb8aa3b, v52
	v_fmac_f32_e32 v114, v118, v114
	v_div_scale_f32 v118, vcc, v105, v106, v105
	v_exp_f32_e32 v56, v56
	v_mul_f32_e32 v122, v118, v114
	v_fma_f32 v123, -v110, v122, v118
	v_fmac_f32_e32 v122, v123, v114
	v_fma_f32 v110, -v110, v122, v118
	v_add_f32_e32 v56, 1.0, v56
	v_div_fmas_f32 v110, v110, v114, v122
	v_div_scale_f32 v60, s[10:11], v56, v56, v52
	v_div_fixup_f32 v105, v110, v106, v105
	v_rcp_f32_e32 v106, v60
	v_ashrrev_i32_e32 v101, 31, v100
	v_ashrrev_i32_e32 v97, 31, v96
	v_ashrrev_i32_e32 v93, 31, v92
	v_fma_f32 v107, -v60, v106, 1.0
	v_fmac_f32_e32 v106, v107, v106
	v_div_scale_f32 v107, vcc, v52, v56, v52
	v_mul_f32_e32 v110, v107, v106
	v_fma_f32 v111, -v60, v110, v107
	v_fmac_f32_e32 v110, v111, v106
	v_fma_f32 v60, -v60, v110, v107
	v_div_fmas_f32 v60, v60, v106, v110
	v_div_fixup_f32 v52, v60, v56, v52
	v_lshlrev_b32_e32 v56, 16, v53
	v_fma_f32 v56, v116, v56, v108
	v_lshlrev_b32_e32 v60, 16, v57
	v_fma_f32 v60, v112, v60, v56
	v_cndmask_b32_e64 v56, v56, v60, s[0:1]
	v_lshlrev_b32_e32 v60, 16, v61
	v_fma_f32 v60, v120, v60, v56
	v_cndmask_b32_e64 v56, v56, v60, s[54:55]
	v_mul_f32_e32 v60, 0xbfb8aa3b, v56
	v_exp_f32_e32 v60, v60
	v_and_b32_e32 v53, 0xffff0000, v53
	v_fmac_f32_e32 v109, v117, v53
	v_and_b32_e32 v53, 0xffff0000, v57
	v_add_f32_e32 v60, 1.0, v60
	v_div_scale_f32 v106, s[10:11], v60, v60, v56
	v_rcp_f32_e32 v107, v106
	v_fma_f32 v53, v113, v53, v109
	v_cndmask_b32_e64 v53, v109, v53, s[0:1]
	v_and_b32_e32 v57, 0xffff0000, v61
	v_fma_f32 v57, v121, v57, v53
	v_fma_f32 v108, -v106, v107, 1.0
	v_cndmask_b32_e64 v53, v53, v57, s[54:55]
	v_fmac_f32_e32 v107, v108, v107
	v_div_scale_f32 v108, vcc, v56, v60, v56
	v_mul_f32_e32 v57, 0xbfb8aa3b, v53
	v_mul_f32_e32 v110, v108, v107
	v_exp_f32_e32 v57, v57
	v_fma_f32 v111, -v106, v110, v108
	v_fmac_f32_e32 v110, v111, v107
	v_fma_f32 v106, -v106, v110, v108
	v_div_fmas_f32 v106, v106, v107, v110
	v_add_f32_e32 v57, 1.0, v57
	v_div_fixup_f32 v56, v106, v60, v56
	v_div_scale_f32 v60, s[10:11], v57, v57, v53
	v_rcp_f32_e32 v61, v60
	v_cvt_pk_bf16_f32 v52, v105, v52
	v_ashrrev_i32_e32 v89, 31, v88
	v_ashrrev_i32_e32 v85, 31, v84
	v_fma_f32 v106, -v60, v61, 1.0
	v_fmac_f32_e32 v61, v106, v61
	v_div_scale_f32 v106, vcc, v53, v57, v53
	v_mul_f32_e32 v107, v106, v61
	v_fma_f32 v108, -v60, v107, v106
	v_fmac_f32_e32 v107, v108, v61
	v_fma_f32 v60, -v60, v107, v106
	v_div_fmas_f32 v60, v60, v61, v107
	v_div_fixup_f32 v53, v60, v57, v53
	v_lshlrev_b32_e32 v57, 16, v54
	v_fma_f32 v57, v72, v57, v64
	v_lshlrev_b32_e32 v60, 16, v58
	v_fma_f32 v60, v68, v60, v57
	v_cndmask_b32_e64 v57, v57, v60, s[0:1]
	v_lshlrev_b32_e32 v60, 16, v62
	s_waitcnt lgkmcnt(0)
	v_fma_f32 v60, v76, v60, v57
	v_cndmask_b32_e64 v57, v57, v60, s[54:55]
	v_mul_f32_e32 v60, 0xbfb8aa3b, v57
	v_exp_f32_e32 v60, v60
	v_and_b32_e32 v54, 0xffff0000, v54
	v_fma_f32 v54, v73, v54, v65
	v_and_b32_e32 v58, 0xffff0000, v58
	v_add_f32_e32 v60, 1.0, v60
	v_div_scale_f32 v61, s[10:11], v60, v60, v57
	v_rcp_f32_e32 v64, v61
	v_fma_f32 v58, v69, v58, v54
	v_cndmask_b32_e64 v54, v54, v58, s[0:1]
	v_and_b32_e32 v58, 0xffff0000, v62
	v_fma_f32 v58, v77, v58, v54
	v_fma_f32 v68, -v61, v64, 1.0
	v_cndmask_b32_e64 v54, v54, v58, s[54:55]
	v_fmac_f32_e32 v64, v68, v64
	v_div_scale_f32 v68, vcc, v57, v60, v57
	v_mul_f32_e32 v58, 0xbfb8aa3b, v54
	v_mul_f32_e32 v72, v68, v64
	v_exp_f32_e32 v58, v58
	v_fma_f32 v76, -v61, v72, v68
	v_fmac_f32_e32 v72, v76, v64
	v_fma_f32 v61, -v61, v72, v68
	v_div_fmas_f32 v61, v61, v64, v72
	v_add_f32_e32 v58, 1.0, v58
	v_div_fixup_f32 v57, v61, v60, v57
	v_div_scale_f32 v60, s[10:11], v58, v58, v54
	v_rcp_f32_e32 v61, v60
	v_cvt_pk_bf16_f32 v53, v56, v53
	s_addk_i32 s76, 0x500
	v_add_u32_e32 v80, 0x2800, v80
	v_fma_f32 v62, -v60, v61, 1.0
	v_fmac_f32_e32 v61, v62, v61
	v_div_scale_f32 v62, vcc, v54, v58, v54
	v_mul_f32_e32 v64, v62, v61
	v_fma_f32 v65, -v60, v64, v62
	v_fmac_f32_e32 v64, v65, v61
	v_fma_f32 v60, -v60, v64, v62
	v_div_fmas_f32 v60, v60, v61, v64
	v_div_fixup_f32 v54, v60, v58, v54
	v_lshlrev_b32_e32 v58, 16, v55
	v_fma_f32 v58, v74, v58, v66
	v_lshlrev_b32_e32 v60, 16, v59
	v_fma_f32 v60, v70, v60, v58
	v_cndmask_b32_e64 v58, v58, v60, s[0:1]
	v_lshlrev_b32_e32 v60, 16, v63
	v_fma_f32 v60, v78, v60, v58
	v_cndmask_b32_e64 v58, v58, v60, s[54:55]
	v_mul_f32_e32 v60, 0xbfb8aa3b, v58
	v_exp_f32_e32 v60, v60
; DI float bf2f(bf16_t v) { return __uint_as_float(((unsigned)v) << 16); }
; DI float silu(float x) { return x / (1.f + __expf(-x)); }
; DI void ssmconv_item(const Params& p, int layer, int it, const float* w, const float* bb) {
;     ...
;         for (int j = 0; j < 5; ++j) { const int i = tid + 256 * (j0 + j), rl = i / 80, c = (i - rl * 80) * 8, t = t0 + rl; const size_t r = r0 + rl;
;             const bool hp = t > 0, hn = t < L - 1;
;             const f32x4 b0 = *(const f32x4*)(bb + c), b1 = *(const f32x4*)(bb + c + 4), wa0 = *(const f32x4*)(w + c), wa1 = *(const f32x4*)(w + c + 4),
;                         wb0 = *(const f32x4*)(w + 640 + c), wb1 = *(const f32x4*)(w + 640 + c + 4), wc0 = *(const f32x4*)(w + 1280 + c), wc1 = *(const f32x4*)(w + 1280 + c + 4);
;             const float bv[8] = { b0.x, b0.y, b0.z, b0.w, b1.x, b1.y, b1.z, b1.w }, w0v[8] = { wa0.x, wa0.y, wa0.z, wa0.w, wa1.x, wa1.y, wa1.z, wa1.w },
;                         w1v[8] = { wb0.x, wb0.y, wb0.z, wb0.w, wb1.x, wb1.y, wb1.z, wb1.w }, w2v[8] = { wc0.x, wc0.y, wc0.z, wc0.w, wc1.x, wc1.y, wc1.z, wc1.w };
;             float o[8];
; #pragma unroll
;             for (int e = 0; e < 8; ++e) { float v = bv[e] + w1v[e] * bf2f((bf16_t)xc[j][e]);
;                 if (hp) v += w0v[e] * bf2f((bf16_t)xp[j][e]);
;                 if (hn) v += w2v[e] * bf2f((bf16_t)xn[j][e]);
;                 o[e] = silu(v); }
;             *(bf16x8*)(UZ + r * 1024 + c) = pack8(o[0], o[1], o[2], o[3], o[4], o[5], o[6], o[7]); }
	v_and_b32_e32 v55, 0xffff0000, v55
	v_fmac_f32_e32 v67, v75, v55
	v_and_b32_e32 v55, 0xffff0000, v59
	v_add_f32_e32 v60, 1.0, v60
	v_div_scale_f32 v61, s[10:11], v60, v60, v58
	v_rcp_f32_e32 v62, v61
	v_fma_f32 v55, v71, v55, v67
	v_cndmask_b32_e64 v55, v67, v55, s[0:1]
	v_and_b32_e32 v59, 0xffff0000, v63
	v_fma_f32 v59, v79, v59, v55
	v_fma_f32 v64, -v61, v62, 1.0
	v_cndmask_b32_e64 v55, v55, v59, s[54:55]
	v_fmac_f32_e32 v62, v64, v62
	v_div_scale_f32 v64, vcc, v58, v60, v58
	v_mul_f32_e32 v59, 0xbfb8aa3b, v55
	v_mul_f32_e32 v65, v64, v62
	v_exp_f32_e32 v59, v59
	v_fma_f32 v66, -v61, v65, v64
	v_fmac_f32_e32 v65, v66, v62
	v_fma_f32 v61, -v61, v65, v64
	v_div_fmas_f32 v61, v61, v62, v65
	v_add_f32_e32 v59, 1.0, v59
	v_div_fixup_f32 v58, v61, v60, v58
	v_div_scale_f32 v60, s[0:1], v59, v59, v55
	v_rcp_f32_e32 v61, v60
	v_cvt_pk_bf16_f32 v54, v57, v54
	v_lshlrev_b64 v[56:57], 11, v[100:101]
	v_lshl_add_u64 v[56:57], s[34:35], 0, v[56:57]
	v_fma_f32 v62, -v60, v61, 1.0
	v_fmac_f32_e32 v61, v62, v61
	v_div_scale_f32 v62, vcc, v55, v59, v55
	v_mul_f32_e32 v63, v62, v61
	v_fma_f32 v64, -v60, v63, v62
	v_fmac_f32_e32 v63, v64, v61
	v_fma_f32 v60, -v60, v63, v62
	v_div_fmas_f32 v60, v60, v61, v63
	v_div_fixup_f32 v55, v60, v59, v55
	v_lshl_add_u64 v[56:57], v[98:99], 1, v[56:57]
	v_cvt_pk_bf16_f32 v55, v58, v55
	global_store_dwordx4 v[56:57], v[52:55], off
	v_mad_u64_u32 v[64:65], s[0:1], v104, s79, v[2:3]
	ds_read_b128 v[68:71], v64 offset:15872
	ds_read_b128 v[52:55], v64 offset:15888
	ds_read_b128 v[72:75], v64 offset:8192
	ds_read_b128 v[56:59], v64 offset:8208
	ds_read_b128 v[76:79], v64 offset:10752
	ds_read_b128 v[60:63], v64 offset:10768
	ds_read_b128 v[98:101], v64 offset:13312
	ds_read_b128 v[64:67], v64 offset:13328
	v_lshlrev_b32_e32 v104, 16, v40
	s_waitcnt lgkmcnt(3)
	v_fma_f32 v68, v76, v104, v68
	v_lshlrev_b32_e32 v76, 16, v44
	v_fma_f32 v72, v72, v76, v68
	v_cndmask_b32_e64 v68, v68, v72, s[48:49]
	v_lshlrev_b32_e32 v72, 16, v48
	s_waitcnt lgkmcnt(1)
	v_fma_f32 v72, v98, v72, v68
	v_cndmask_b32_e64 v68, v68, v72, s[50:51]
	v_mul_f32_e32 v72, 0xbfb8aa3b, v68
	v_exp_f32_e32 v72, v72
	v_and_b32_e32 v40, 0xffff0000, v40
	v_fma_f32 v40, v77, v40, v69
	v_and_b32_e32 v44, 0xffff0000, v44
	v_fma_f32 v44, v73, v44, v40
	v_cndmask_b32_e64 v40, v40, v44, s[48:49]
	v_and_b32_e32 v44, 0xffff0000, v48
	v_add_f32_e32 v72, 1.0, v72
	v_fma_f32 v44, v99, v44, v40
	v_div_scale_f32 v76, s[0:1], v72, v72, v68
	v_cndmask_b32_e64 v40, v40, v44, s[50:51]
	v_rcp_f32_e32 v98, v76
	v_mul_f32_e32 v44, 0xbfb8aa3b, v40
	v_exp_f32_e32 v44, v44
	v_fma_f32 v104, -v76, v98, 1.0
	v_fmac_f32_e32 v98, v104, v98
	v_div_scale_f32 v104, vcc, v68, v72, v68
	v_add_f32_e32 v44, 1.0, v44
	v_mul_f32_e32 v105, v104, v98
	v_div_scale_f32 v48, s[0:1], v44, v44, v40
	v_fma_f32 v106, -v76, v105, v104
	v_rcp_f32_e32 v69, v48
	v_fmac_f32_e32 v105, v106, v98
	v_fma_f32 v76, -v76, v105, v104
	v_div_fmas_f32 v76, v76, v98, v105
	v_div_fixup_f32 v68, v76, v72, v68
	v_fma_f32 v72, -v48, v69, 1.0
	v_fmac_f32_e32 v69, v72, v69
	v_div_scale_f32 v72, vcc, v40, v44, v40
	v_mul_f32_e32 v73, v72, v69
	v_fma_f32 v76, -v48, v73, v72
	v_fmac_f32_e32 v73, v76, v69
	v_fma_f32 v48, -v48, v73, v72
	v_div_fmas_f32 v48, v48, v69, v73
	v_div_fixup_f32 v40, v48, v44, v40
	v_lshlrev_b32_e32 v44, 16, v41
	v_fma_f32 v44, v78, v44, v70
	v_lshlrev_b32_e32 v48, 16, v45
	v_fma_f32 v48, v74, v48, v44
	v_cndmask_b32_e64 v44, v44, v48, s[48:49]
	v_lshlrev_b32_e32 v48, 16, v49
	v_fma_f32 v48, v100, v48, v44
	v_cndmask_b32_e64 v44, v44, v48, s[50:51]
	v_mul_f32_e32 v48, 0xbfb8aa3b, v44
	v_exp_f32_e32 v48, v48
	v_and_b32_e32 v41, 0xffff0000, v41
	v_fmac_f32_e32 v71, v79, v41
	v_and_b32_e32 v41, 0xffff0000, v45
	v_add_f32_e32 v48, 1.0, v48
	v_div_scale_f32 v69, s[0:1], v48, v48, v44
	v_rcp_f32_e32 v70, v69
	v_fma_f32 v41, v75, v41, v71
	v_cndmask_b32_e64 v41, v71, v41, s[48:49]
	v_and_b32_e32 v45, 0xffff0000, v49
	v_fma_f32 v45, v101, v45, v41
	v_fma_f32 v72, -v69, v70, 1.0
	v_cndmask_b32_e64 v41, v41, v45, s[50:51]
	v_fmac_f32_e32 v70, v72, v70
	v_div_scale_f32 v72, vcc, v44, v48, v44
	v_mul_f32_e32 v45, 0xbfb8aa3b, v41
	v_mul_f32_e32 v73, v72, v70
	v_exp_f32_e32 v45, v45
	v_fma_f32 v74, -v69, v73, v72
	v_fmac_f32_e32 v73, v74, v70
	v_fma_f32 v69, -v69, v73, v72
	v_div_fmas_f32 v69, v69, v70, v73
	v_add_f32_e32 v45, 1.0, v45
	v_div_fixup_f32 v44, v69, v48, v44
	v_div_scale_f32 v48, s[0:1], v45, v45, v41
	v_rcp_f32_e32 v49, v48
	v_cvt_pk_bf16_f32 v40, v68, v40
	v_lshlrev_b32_e32 v72, 16, v28
	v_and_b32_e32 v28, 0xffff0000, v28
	v_fma_f32 v69, -v48, v49, 1.0
	v_fmac_f32_e32 v49, v69, v49
	v_div_scale_f32 v69, vcc, v41, v45, v41
	v_mul_f32_e32 v70, v69, v49
	v_fma_f32 v71, -v48, v70, v69
	v_fmac_f32_e32 v70, v71, v49
	v_fma_f32 v48, -v48, v70, v69
	v_div_fmas_f32 v48, v48, v49, v70
	v_div_fixup_f32 v41, v48, v45, v41
	v_lshlrev_b32_e32 v45, 16, v42
	v_fma_f32 v45, v60, v45, v52
	v_lshlrev_b32_e32 v48, 16, v46
	v_fma_f32 v48, v56, v48, v45
	v_cndmask_b32_e64 v45, v45, v48, s[48:49]
	v_lshlrev_b32_e32 v48, 16, v50
	s_waitcnt lgkmcnt(0)
; DI float bf2f(bf16_t v) { return __uint_as_float(((unsigned)v) << 16); }
; DI float silu(float x) { return x / (1.f + __expf(-x)); }
; DI void ssmconv_item(const Params& p, int layer, int it, const float* w, const float* bb) {
;     ...
;         for (int j = 0; j < 5; ++j) { const int i = tid + 256 * (j0 + j), rl = i / 80, c = (i - rl * 80) * 8, t = t0 + rl; const size_t r = r0 + rl;
;             const bool hp = t > 0, hn = t < L - 1;
;             const f32x4 b0 = *(const f32x4*)(bb + c), b1 = *(const f32x4*)(bb + c + 4), wa0 = *(const f32x4*)(w + c), wa1 = *(const f32x4*)(w + c + 4),
;                         wb0 = *(const f32x4*)(w + 640 + c), wb1 = *(const f32x4*)(w + 640 + c + 4), wc0 = *(const f32x4*)(w + 1280 + c), wc1 = *(const f32x4*)(w + 1280 + c + 4);
;             const float bv[8] = { b0.x, b0.y, b0.z, b0.w, b1.x, b1.y, b1.z, b1.w }, w0v[8] = { wa0.x, wa0.y, wa0.z, wa0.w, wa1.x, wa1.y, wa1.z, wa1.w },
;                         w1v[8] = { wb0.x, wb0.y, wb0.z, wb0.w, wb1.x, wb1.y, wb1.z, wb1.w }, w2v[8] = { wc0.x, wc0.y, wc0.z, wc0.w, wc1.x, wc1.y, wc1.z, wc1.w };
;             float o[8];
; #pragma unroll
;             for (int e = 0; e < 8; ++e) { float v = bv[e] + w1v[e] * bf2f((bf16_t)xc[j][e]);
;                 if (hp) v += w0v[e] * bf2f((bf16_t)xp[j][e]);
;                 if (hn) v += w2v[e] * bf2f((bf16_t)xn[j][e]);
;                 o[e] = silu(v); }
;             *(bf16x8*)(UZ + r * 1024 + c) = pack8(o[0], o[1], o[2], o[3], o[4], o[5], o[6], o[7]); }
	v_fma_f32 v48, v64, v48, v45
	v_cndmask_b32_e64 v45, v45, v48, s[50:51]
	v_mul_f32_e32 v48, 0xbfb8aa3b, v45
	v_exp_f32_e32 v48, v48
	v_and_b32_e32 v42, 0xffff0000, v42
	v_fma_f32 v42, v61, v42, v53
	v_and_b32_e32 v46, 0xffff0000, v46
	v_add_f32_e32 v48, 1.0, v48
	v_div_scale_f32 v49, s[0:1], v48, v48, v45
	v_rcp_f32_e32 v52, v49
	v_fma_f32 v46, v57, v46, v42
	v_cndmask_b32_e64 v42, v42, v46, s[48:49]
	v_and_b32_e32 v46, 0xffff0000, v50
	v_fma_f32 v46, v65, v46, v42
	v_fma_f32 v56, -v49, v52, 1.0
	v_cndmask_b32_e64 v42, v42, v46, s[50:51]
	v_fmac_f32_e32 v52, v56, v52
	v_div_scale_f32 v56, vcc, v45, v48, v45
	v_mul_f32_e32 v46, 0xbfb8aa3b, v42
	v_mul_f32_e32 v60, v56, v52
	v_exp_f32_e32 v46, v46
	v_fma_f32 v64, -v49, v60, v56
	v_fmac_f32_e32 v60, v64, v52
	v_fma_f32 v49, -v49, v60, v56
	v_div_fmas_f32 v49, v49, v52, v60
	v_add_f32_e32 v46, 1.0, v46
	v_div_fixup_f32 v45, v49, v48, v45
	v_div_scale_f32 v48, s[0:1], v46, v46, v42
	v_rcp_f32_e32 v49, v48
	v_cvt_pk_bf16_f32 v41, v44, v41
	s_nop 0
	v_fma_f32 v50, -v48, v49, 1.0
	v_fmac_f32_e32 v49, v50, v49
	v_div_scale_f32 v50, vcc, v42, v46, v42
	v_mul_f32_e32 v52, v50, v49
	v_fma_f32 v53, -v48, v52, v50
	v_fmac_f32_e32 v52, v53, v49
	v_fma_f32 v48, -v48, v52, v50
	v_div_fmas_f32 v48, v48, v49, v52
	v_div_fixup_f32 v42, v48, v46, v42
	v_lshlrev_b32_e32 v46, 16, v43
	v_fma_f32 v46, v62, v46, v54
	v_lshlrev_b32_e32 v48, 16, v47
	v_fma_f32 v48, v58, v48, v46
	v_cndmask_b32_e64 v46, v46, v48, s[48:49]
	v_lshlrev_b32_e32 v48, 16, v51
	v_fma_f32 v48, v66, v48, v46
	v_cndmask_b32_e64 v46, v46, v48, s[50:51]
	v_mul_f32_e32 v48, 0xbfb8aa3b, v46
	v_exp_f32_e32 v48, v48
	v_and_b32_e32 v43, 0xffff0000, v43
	v_fmac_f32_e32 v55, v63, v43
	v_and_b32_e32 v43, 0xffff0000, v47
	v_add_f32_e32 v48, 1.0, v48
	v_div_scale_f32 v49, s[0:1], v48, v48, v46
	v_rcp_f32_e32 v50, v49
	v_fma_f32 v43, v59, v43, v55
	v_cndmask_b32_e64 v43, v55, v43, s[48:49]
	v_and_b32_e32 v47, 0xffff0000, v51
	v_fma_f32 v47, v67, v47, v43
	v_fma_f32 v52, -v49, v50, 1.0
	v_cndmask_b32_e64 v43, v43, v47, s[50:51]
	v_fmac_f32_e32 v50, v52, v50
	v_div_scale_f32 v52, vcc, v46, v48, v46
	v_mul_f32_e32 v47, 0xbfb8aa3b, v43
	v_mul_f32_e32 v53, v52, v50
	v_exp_f32_e32 v47, v47
	v_fma_f32 v54, -v49, v53, v52
	v_fmac_f32_e32 v53, v54, v50
	v_fma_f32 v49, -v49, v53, v52
	v_div_fmas_f32 v49, v49, v50, v53
	v_add_f32_e32 v47, 1.0, v47
	v_div_fixup_f32 v46, v49, v48, v46
	v_div_scale_f32 v48, s[0:1], v47, v47, v43
	v_rcp_f32_e32 v49, v48
	v_cvt_pk_bf16_f32 v42, v45, v42
	v_lshlrev_b64 v[44:45], 11, v[96:97]
	v_lshl_add_u64 v[44:45], s[34:35], 0, v[44:45]
	v_fma_f32 v50, -v48, v49, 1.0
	v_fmac_f32_e32 v49, v50, v49
	v_div_scale_f32 v50, vcc, v43, v47, v43
	v_mul_f32_e32 v51, v50, v49
	v_fma_f32 v52, -v48, v51, v50
	v_fmac_f32_e32 v51, v52, v49
	v_fma_f32 v48, -v48, v51, v50
	v_div_fmas_f32 v48, v48, v49, v51
	v_div_fixup_f32 v43, v48, v47, v43
	v_lshl_add_u64 v[44:45], v[94:95], 1, v[44:45]
	v_cvt_pk_bf16_f32 v43, v46, v43
	global_store_dwordx4 v[44:45], v[40:43], off
	v_mad_u64_u32 v[52:53], s[0:1], v103, s79, v[2:3]
	ds_read_b128 v[56:59], v52 offset:24064
	ds_read_b128 v[40:43], v52 offset:24080
	ds_read_b128 v[60:63], v52 offset:16384
	ds_read_b128 v[44:47], v52 offset:16400
	ds_read_b128 v[64:67], v52 offset:18944
	ds_read_b128 v[48:51], v52 offset:18960
	ds_read_b128 v[68:71], v52 offset:21504
	ds_read_b128 v[52:55], v52 offset:21520
	s_waitcnt lgkmcnt(3)
	v_fma_f32 v56, v64, v72, v56
	v_lshlrev_b32_e32 v64, 16, v32
	v_fma_f32 v60, v60, v64, v56
	v_cndmask_b32_e64 v56, v56, v60, s[44:45]
	v_lshlrev_b32_e32 v60, 16, v36
	s_waitcnt lgkmcnt(1)
	v_fma_f32 v60, v68, v60, v56
	v_cndmask_b32_e64 v56, v56, v60, s[46:47]
	v_mul_f32_e32 v60, 0xbfb8aa3b, v56
	v_exp_f32_e32 v60, v60
	v_fma_f32 v28, v65, v28, v57
	v_and_b32_e32 v32, 0xffff0000, v32
	v_fma_f32 v32, v61, v32, v28
	v_cndmask_b32_e64 v28, v28, v32, s[44:45]
	v_and_b32_e32 v32, 0xffff0000, v36
	v_add_f32_e32 v60, 1.0, v60
	v_fma_f32 v32, v69, v32, v28
	v_div_scale_f32 v64, s[0:1], v60, v60, v56
	v_cndmask_b32_e64 v28, v28, v32, s[46:47]
	v_rcp_f32_e32 v68, v64
	v_mul_f32_e32 v32, 0xbfb8aa3b, v28
	v_exp_f32_e32 v32, v32
	v_fma_f32 v72, -v64, v68, 1.0
	v_fmac_f32_e32 v68, v72, v68
	v_div_scale_f32 v72, vcc, v56, v60, v56
	v_add_f32_e32 v32, 1.0, v32
	v_mul_f32_e32 v73, v72, v68
	v_div_scale_f32 v36, s[0:1], v32, v32, v28
	v_fma_f32 v74, -v64, v73, v72
	v_rcp_f32_e32 v57, v36
	v_fmac_f32_e32 v73, v74, v68
	v_fma_f32 v64, -v64, v73, v72
	v_div_fmas_f32 v64, v64, v68, v73
	v_div_fixup_f32 v56, v64, v60, v56
	v_fma_f32 v60, -v36, v57, 1.0
	v_fmac_f32_e32 v57, v60, v57
	v_div_scale_f32 v60, vcc, v28, v32, v28
	v_mul_f32_e32 v61, v60, v57
	v_fma_f32 v64, -v36, v61, v60
	v_fmac_f32_e32 v61, v64, v57
	v_fma_f32 v36, -v36, v61, v60
	v_div_fmas_f32 v36, v36, v57, v61
	v_div_fixup_f32 v28, v36, v32, v28
	v_lshlrev_b32_e32 v32, 16, v29
	v_fma_f32 v32, v66, v32, v58
	v_lshlrev_b32_e32 v36, 16, v33
	v_fma_f32 v36, v62, v36, v32
	v_cndmask_b32_e64 v32, v32, v36, s[44:45]
	v_lshlrev_b32_e32 v36, 16, v37
	v_fma_f32 v36, v70, v36, v32
	v_cndmask_b32_e64 v32, v32, v36, s[46:47]
	v_mul_f32_e32 v36, 0xbfb8aa3b, v32
	v_exp_f32_e32 v36, v36
	v_and_b32_e32 v29, 0xffff0000, v29
	v_fmac_f32_e32 v59, v67, v29
	v_and_b32_e32 v29, 0xffff0000, v33
	v_add_f32_e32 v36, 1.0, v36
	v_div_scale_f32 v57, s[0:1], v36, v36, v32
	v_rcp_f32_e32 v58, v57
	v_fma_f32 v29, v63, v29, v59
	v_cndmask_b32_e64 v29, v59, v29, s[44:45]
	v_and_b32_e32 v33, 0xffff0000, v37
	v_fma_f32 v33, v71, v33, v29
	v_fma_f32 v60, -v57, v58, 1.0
	v_cndmask_b32_e64 v29, v29, v33, s[46:47]
	v_fmac_f32_e32 v58, v60, v58
	v_div_scale_f32 v60, vcc, v32, v36, v32
	v_mul_f32_e32 v33, 0xbfb8aa3b, v29
	v_mul_f32_e32 v61, v60, v58
	v_exp_f32_e32 v33, v33
	v_fma_f32 v62, -v57, v61, v60
	v_fmac_f32_e32 v61, v62, v58
	v_fma_f32 v57, -v57, v61, v60
	v_div_fmas_f32 v57, v57, v58, v61
	v_add_f32_e32 v33, 1.0, v33
	v_div_fixup_f32 v32, v57, v36, v32
	v_div_scale_f32 v36, s[0:1], v33, v33, v29
	v_rcp_f32_e32 v37, v36
	v_cvt_pk_bf16_f32 v28, v56, v28
	v_lshlrev_b32_e32 v60, 16, v16
	v_and_b32_e32 v16, 0xffff0000, v16
	v_fma_f32 v57, -v36, v37, 1.0
	v_fmac_f32_e32 v37, v57, v37
	v_div_scale_f32 v57, vcc, v29, v33, v29
	v_mul_f32_e32 v58, v57, v37
	v_fma_f32 v59, -v36, v58, v57
	v_fmac_f32_e32 v58, v59, v37
	v_fma_f32 v36, -v36, v58, v57
	v_div_fmas_f32 v36, v36, v37, v58
	v_div_fixup_f32 v29, v36, v33, v29
	v_lshlrev_b32_e32 v33, 16, v30
	v_fma_f32 v33, v48, v33, v40
	v_lshlrev_b32_e32 v36, 16, v34
	v_fma_f32 v36, v44, v36, v33
	v_cndmask_b32_e64 v33, v33, v36, s[44:45]
	v_lshlrev_b32_e32 v36, 16, v38
	s_waitcnt lgkmcnt(0)
; DI float bf2f(bf16_t v) { return __uint_as_float(((unsigned)v) << 16); }
; DI float silu(float x) { return x / (1.f + __expf(-x)); }
; DI void ssmconv_item(const Params& p, int layer, int it, const float* w, const float* bb) {
;     ...
;         for (int j = 0; j < 5; ++j) { const int i = tid + 256 * (j0 + j), rl = i / 80, c = (i - rl * 80) * 8, t = t0 + rl; const size_t r = r0 + rl;
;             const bool hp = t > 0, hn = t < L - 1;
;             const f32x4 b0 = *(const f32x4*)(bb + c), b1 = *(const f32x4*)(bb + c + 4), wa0 = *(const f32x4*)(w + c), wa1 = *(const f32x4*)(w + c + 4),
;                         wb0 = *(const f32x4*)(w + 640 + c), wb1 = *(const f32x4*)(w + 640 + c + 4), wc0 = *(const f32x4*)(w + 1280 + c), wc1 = *(const f32x4*)(w + 1280 + c + 4);
;             const float bv[8] = { b0.x, b0.y, b0.z, b0.w, b1.x, b1.y, b1.z, b1.w }, w0v[8] = { wa0.x, wa0.y, wa0.z, wa0.w, wa1.x, wa1.y, wa1.z, wa1.w },
;                         w1v[8] = { wb0.x, wb0.y, wb0.z, wb0.w, wb1.x, wb1.y, wb1.z, wb1.w }, w2v[8] = { wc0.x, wc0.y, wc0.z, wc0.w, wc1.x, wc1.y, wc1.z, wc1.w };
;             float o[8];
; #pragma unroll
;             for (int e = 0; e < 8; ++e) { float v = bv[e] + w1v[e] * bf2f((bf16_t)xc[j][e]);
;                 if (hp) v += w0v[e] * bf2f((bf16_t)xp[j][e]);
;                 if (hn) v += w2v[e] * bf2f((bf16_t)xn[j][e]);
;                 o[e] = silu(v); }
;             *(bf16x8*)(UZ + r * 1024 + c) = pack8(o[0], o[1], o[2], o[3], o[4], o[5], o[6], o[7]); }
	v_fma_f32 v36, v52, v36, v33
	v_cndmask_b32_e64 v33, v33, v36, s[46:47]
	v_mul_f32_e32 v36, 0xbfb8aa3b, v33
	v_exp_f32_e32 v36, v36
	v_and_b32_e32 v30, 0xffff0000, v30
	v_fma_f32 v30, v49, v30, v41
	v_and_b32_e32 v34, 0xffff0000, v34
	v_add_f32_e32 v36, 1.0, v36
	v_div_scale_f32 v37, s[0:1], v36, v36, v33
	v_rcp_f32_e32 v40, v37
	v_fma_f32 v34, v45, v34, v30
	v_cndmask_b32_e64 v30, v30, v34, s[44:45]
	v_and_b32_e32 v34, 0xffff0000, v38
	v_fma_f32 v34, v53, v34, v30
	v_fma_f32 v44, -v37, v40, 1.0
	v_cndmask_b32_e64 v30, v30, v34, s[46:47]
	v_fmac_f32_e32 v40, v44, v40
	v_div_scale_f32 v44, vcc, v33, v36, v33
	v_mul_f32_e32 v34, 0xbfb8aa3b, v30
	v_mul_f32_e32 v48, v44, v40
	v_exp_f32_e32 v34, v34
	v_fma_f32 v52, -v37, v48, v44
	v_fmac_f32_e32 v48, v52, v40
	v_fma_f32 v37, -v37, v48, v44
	v_div_fmas_f32 v37, v37, v40, v48
	v_add_f32_e32 v34, 1.0, v34
	v_div_fixup_f32 v33, v37, v36, v33
	v_div_scale_f32 v36, s[0:1], v34, v34, v30
	v_rcp_f32_e32 v37, v36
	v_cvt_pk_bf16_f32 v29, v32, v29
	s_nop 0
	v_fma_f32 v38, -v36, v37, 1.0
	v_fmac_f32_e32 v37, v38, v37
	v_div_scale_f32 v38, vcc, v30, v34, v30
	v_mul_f32_e32 v40, v38, v37
	v_fma_f32 v41, -v36, v40, v38
	v_fmac_f32_e32 v40, v41, v37
	v_fma_f32 v36, -v36, v40, v38
	v_div_fmas_f32 v36, v36, v37, v40
	v_div_fixup_f32 v30, v36, v34, v30
	v_lshlrev_b32_e32 v34, 16, v31
	v_fma_f32 v34, v50, v34, v42
	v_lshlrev_b32_e32 v36, 16, v35
	v_fma_f32 v36, v46, v36, v34
	v_cndmask_b32_e64 v34, v34, v36, s[44:45]
	v_lshlrev_b32_e32 v36, 16, v39
	v_fma_f32 v36, v54, v36, v34
	v_cndmask_b32_e64 v34, v34, v36, s[46:47]
	v_mul_f32_e32 v36, 0xbfb8aa3b, v34
	v_exp_f32_e32 v36, v36
	v_and_b32_e32 v31, 0xffff0000, v31
	v_fmac_f32_e32 v43, v51, v31
	v_and_b32_e32 v31, 0xffff0000, v35
	v_add_f32_e32 v36, 1.0, v36
	v_div_scale_f32 v37, s[0:1], v36, v36, v34
	v_rcp_f32_e32 v38, v37
	v_fma_f32 v31, v47, v31, v43
	v_cndmask_b32_e64 v31, v43, v31, s[44:45]
	v_and_b32_e32 v35, 0xffff0000, v39
	v_fma_f32 v35, v55, v35, v31
	v_fma_f32 v40, -v37, v38, 1.0
	v_cndmask_b32_e64 v31, v31, v35, s[46:47]
	v_fmac_f32_e32 v38, v40, v38
	v_div_scale_f32 v40, vcc, v34, v36, v34
	v_mul_f32_e32 v35, 0xbfb8aa3b, v31
	v_mul_f32_e32 v41, v40, v38
	v_exp_f32_e32 v35, v35
	v_fma_f32 v42, -v37, v41, v40
	v_fmac_f32_e32 v41, v42, v38
	v_fma_f32 v37, -v37, v41, v40
	v_div_fmas_f32 v37, v37, v38, v41
	v_add_f32_e32 v35, 1.0, v35
	v_div_fixup_f32 v34, v37, v36, v34
	v_div_scale_f32 v36, s[0:1], v35, v35, v31
	v_rcp_f32_e32 v37, v36
	v_cvt_pk_bf16_f32 v30, v33, v30
	v_lshlrev_b64 v[32:33], 11, v[92:93]
	v_lshl_add_u64 v[32:33], s[34:35], 0, v[32:33]
	v_fma_f32 v38, -v36, v37, 1.0
	v_fmac_f32_e32 v37, v38, v37
	v_div_scale_f32 v38, vcc, v31, v35, v31
	v_mul_f32_e32 v39, v38, v37
	v_fma_f32 v40, -v36, v39, v38
	v_fmac_f32_e32 v39, v40, v37
	v_fma_f32 v36, -v36, v39, v38
	v_div_fmas_f32 v36, v36, v37, v39
	v_div_fixup_f32 v31, v36, v35, v31
	v_lshl_add_u64 v[32:33], v[90:91], 1, v[32:33]
	v_cvt_pk_bf16_f32 v31, v34, v31
	global_store_dwordx4 v[32:33], v[28:31], off
	v_mad_u64_u32 v[40:41], s[0:1], v102, s79, v[2:3]
	ds_read_b128 v[44:47], v40 offset:32256
	ds_read_b128 v[28:31], v40 offset:32272
	ds_read_b128 v[48:51], v40 offset:24576
	ds_read_b128 v[32:35], v40 offset:24592
	ds_read_b128 v[52:55], v40 offset:27136
	ds_read_b128 v[36:39], v40 offset:27152
	ds_read_b128 v[56:59], v40 offset:29696
	ds_read_b128 v[40:43], v40 offset:29712
	s_waitcnt lgkmcnt(3)
	v_fma_f32 v44, v52, v60, v44
	v_lshlrev_b32_e32 v52, 16, v20
	v_fma_f32 v48, v48, v52, v44
	v_cndmask_b32_e64 v44, v44, v48, s[40:41]
	v_lshlrev_b32_e32 v48, 16, v24
	s_waitcnt lgkmcnt(1)
	v_fma_f32 v48, v56, v48, v44
	v_cndmask_b32_e64 v44, v44, v48, s[42:43]
	v_mul_f32_e32 v48, 0xbfb8aa3b, v44
	v_exp_f32_e32 v48, v48
	v_fma_f32 v16, v53, v16, v45
	v_and_b32_e32 v20, 0xffff0000, v20
	v_fma_f32 v20, v49, v20, v16
	v_cndmask_b32_e64 v16, v16, v20, s[40:41]
	v_and_b32_e32 v20, 0xffff0000, v24
	v_add_f32_e32 v48, 1.0, v48
	v_fma_f32 v20, v57, v20, v16
	v_div_scale_f32 v52, s[0:1], v48, v48, v44
	v_cndmask_b32_e64 v16, v16, v20, s[42:43]
	v_rcp_f32_e32 v56, v52
	v_mul_f32_e32 v20, 0xbfb8aa3b, v16
	v_exp_f32_e32 v20, v20
	v_fma_f32 v60, -v52, v56, 1.0
	v_fmac_f32_e32 v56, v60, v56
	v_div_scale_f32 v60, vcc, v44, v48, v44
	v_add_f32_e32 v20, 1.0, v20
	v_mul_f32_e32 v61, v60, v56
	v_div_scale_f32 v24, s[0:1], v20, v20, v16
	v_fma_f32 v62, -v52, v61, v60
	v_rcp_f32_e32 v45, v24
	v_fmac_f32_e32 v61, v62, v56
	v_fma_f32 v52, -v52, v61, v60
	v_div_fmas_f32 v52, v52, v56, v61
	v_div_fixup_f32 v44, v52, v48, v44
	v_fma_f32 v48, -v24, v45, 1.0
	v_fmac_f32_e32 v45, v48, v45
	v_div_scale_f32 v48, vcc, v16, v20, v16
	v_mul_f32_e32 v49, v48, v45
	v_fma_f32 v52, -v24, v49, v48
	v_fmac_f32_e32 v49, v52, v45
	v_fma_f32 v24, -v24, v49, v48
	v_div_fmas_f32 v24, v24, v45, v49
	v_div_fixup_f32 v16, v24, v20, v16
	v_lshlrev_b32_e32 v20, 16, v17
	v_fma_f32 v20, v54, v20, v46
	v_lshlrev_b32_e32 v24, 16, v21
	v_fma_f32 v24, v50, v24, v20
	v_cndmask_b32_e64 v20, v20, v24, s[40:41]
	v_lshlrev_b32_e32 v24, 16, v25
	v_fma_f32 v24, v58, v24, v20
	v_cndmask_b32_e64 v20, v20, v24, s[42:43]
	v_mul_f32_e32 v24, 0xbfb8aa3b, v20
	v_exp_f32_e32 v24, v24
	v_and_b32_e32 v17, 0xffff0000, v17
	v_fmac_f32_e32 v47, v55, v17
	v_and_b32_e32 v17, 0xffff0000, v21
	v_add_f32_e32 v24, 1.0, v24
	v_div_scale_f32 v45, s[0:1], v24, v24, v20
	v_rcp_f32_e32 v46, v45
	v_fma_f32 v17, v51, v17, v47
	v_cndmask_b32_e64 v17, v47, v17, s[40:41]
	v_and_b32_e32 v21, 0xffff0000, v25
	v_fma_f32 v21, v59, v21, v17
	v_fma_f32 v48, -v45, v46, 1.0
	v_cndmask_b32_e64 v17, v17, v21, s[42:43]
	v_fmac_f32_e32 v46, v48, v46
	v_div_scale_f32 v48, vcc, v20, v24, v20
	v_mul_f32_e32 v21, 0xbfb8aa3b, v17
	v_mul_f32_e32 v49, v48, v46
	v_exp_f32_e32 v21, v21
	v_fma_f32 v50, -v45, v49, v48
	v_fmac_f32_e32 v49, v50, v46
	v_fma_f32 v45, -v45, v49, v48
	v_div_fmas_f32 v45, v45, v46, v49
	v_add_f32_e32 v21, 1.0, v21
	v_div_fixup_f32 v20, v45, v24, v20
	v_div_scale_f32 v24, s[0:1], v21, v21, v17
	v_rcp_f32_e32 v25, v24
	v_cvt_pk_bf16_f32 v16, v44, v16
	v_lshlrev_b32_e32 v48, 16, v4
	v_and_b32_e32 v4, 0xffff0000, v4
	v_fma_f32 v45, -v24, v25, 1.0
	v_fmac_f32_e32 v25, v45, v25
	v_div_scale_f32 v45, vcc, v17, v21, v17
	v_mul_f32_e32 v46, v45, v25
	v_fma_f32 v47, -v24, v46, v45
	v_fmac_f32_e32 v46, v47, v25
	v_fma_f32 v24, -v24, v46, v45
	v_div_fmas_f32 v24, v24, v25, v46
	v_div_fixup_f32 v17, v24, v21, v17
	v_lshlrev_b32_e32 v21, 16, v18
	v_fma_f32 v21, v36, v21, v28
	v_lshlrev_b32_e32 v24, 16, v22
	v_fma_f32 v24, v32, v24, v21
	v_cndmask_b32_e64 v21, v21, v24, s[40:41]
	v_lshlrev_b32_e32 v24, 16, v26
	s_waitcnt lgkmcnt(0)
; DI float bf2f(bf16_t v) { return __uint_as_float(((unsigned)v) << 16); }
; DI float silu(float x) { return x / (1.f + __expf(-x)); }
; DI void ssmconv_item(const Params& p, int layer, int it, const float* w, const float* bb) {
;     ...
;         for (int j = 0; j < 5; ++j) { const int i = tid + 256 * (j0 + j), rl = i / 80, c = (i - rl * 80) * 8, t = t0 + rl; const size_t r = r0 + rl;
;             const bool hp = t > 0, hn = t < L - 1;
;             const f32x4 b0 = *(const f32x4*)(bb + c), b1 = *(const f32x4*)(bb + c + 4), wa0 = *(const f32x4*)(w + c), wa1 = *(const f32x4*)(w + c + 4),
;                         wb0 = *(const f32x4*)(w + 640 + c), wb1 = *(const f32x4*)(w + 640 + c + 4), wc0 = *(const f32x4*)(w + 1280 + c), wc1 = *(const f32x4*)(w + 1280 + c + 4);
;             const float bv[8] = { b0.x, b0.y, b0.z, b0.w, b1.x, b1.y, b1.z, b1.w }, w0v[8] = { wa0.x, wa0.y, wa0.z, wa0.w, wa1.x, wa1.y, wa1.z, wa1.w },
;                         w1v[8] = { wb0.x, wb0.y, wb0.z, wb0.w, wb1.x, wb1.y, wb1.z, wb1.w }, w2v[8] = { wc0.x, wc0.y, wc0.z, wc0.w, wc1.x, wc1.y, wc1.z, wc1.w };
;             float o[8];
; #pragma unroll
;             for (int e = 0; e < 8; ++e) { float v = bv[e] + w1v[e] * bf2f((bf16_t)xc[j][e]);
;                 if (hp) v += w0v[e] * bf2f((bf16_t)xp[j][e]);
;                 if (hn) v += w2v[e] * bf2f((bf16_t)xn[j][e]);
;                 o[e] = silu(v); }
;             *(bf16x8*)(UZ + r * 1024 + c) = pack8(o[0], o[1], o[2], o[3], o[4], o[5], o[6], o[7]); }
	v_fma_f32 v24, v40, v24, v21
	v_cndmask_b32_e64 v21, v21, v24, s[42:43]
	v_mul_f32_e32 v24, 0xbfb8aa3b, v21
	v_exp_f32_e32 v24, v24
	v_and_b32_e32 v18, 0xffff0000, v18
	v_fma_f32 v18, v37, v18, v29
	v_and_b32_e32 v22, 0xffff0000, v22
	v_add_f32_e32 v24, 1.0, v24
	v_div_scale_f32 v25, s[0:1], v24, v24, v21
	v_rcp_f32_e32 v28, v25
	v_fma_f32 v22, v33, v22, v18
	v_cndmask_b32_e64 v18, v18, v22, s[40:41]
	v_and_b32_e32 v22, 0xffff0000, v26
	v_fma_f32 v22, v41, v22, v18
	v_fma_f32 v32, -v25, v28, 1.0
	v_cndmask_b32_e64 v18, v18, v22, s[42:43]
	v_fmac_f32_e32 v28, v32, v28
	v_div_scale_f32 v32, vcc, v21, v24, v21
	v_mul_f32_e32 v22, 0xbfb8aa3b, v18
	v_mul_f32_e32 v36, v32, v28
	v_exp_f32_e32 v22, v22
	v_fma_f32 v40, -v25, v36, v32
	v_fmac_f32_e32 v36, v40, v28
	v_fma_f32 v25, -v25, v36, v32
	v_div_fmas_f32 v25, v25, v28, v36
	v_add_f32_e32 v22, 1.0, v22
	v_div_fixup_f32 v21, v25, v24, v21
	v_div_scale_f32 v24, s[0:1], v22, v22, v18
	v_rcp_f32_e32 v25, v24
	v_cvt_pk_bf16_f32 v17, v20, v17
	s_nop 0
	v_fma_f32 v26, -v24, v25, 1.0
	v_fmac_f32_e32 v25, v26, v25
	v_div_scale_f32 v26, vcc, v18, v22, v18
	v_mul_f32_e32 v28, v26, v25
	v_fma_f32 v29, -v24, v28, v26
	v_fmac_f32_e32 v28, v29, v25
	v_fma_f32 v24, -v24, v28, v26
	v_div_fmas_f32 v24, v24, v25, v28
	v_div_fixup_f32 v18, v24, v22, v18
	v_lshlrev_b32_e32 v22, 16, v19
	v_fma_f32 v22, v38, v22, v30
	v_lshlrev_b32_e32 v24, 16, v23
	v_fma_f32 v24, v34, v24, v22
	v_cndmask_b32_e64 v22, v22, v24, s[40:41]
	v_lshlrev_b32_e32 v24, 16, v27
	v_fma_f32 v24, v42, v24, v22
	v_cndmask_b32_e64 v22, v22, v24, s[42:43]
	v_mul_f32_e32 v24, 0xbfb8aa3b, v22
	v_exp_f32_e32 v24, v24
	v_and_b32_e32 v19, 0xffff0000, v19
	v_fmac_f32_e32 v31, v39, v19
	v_and_b32_e32 v19, 0xffff0000, v23
	v_add_f32_e32 v24, 1.0, v24
	v_div_scale_f32 v25, s[0:1], v24, v24, v22
	v_rcp_f32_e32 v26, v25
	v_fma_f32 v19, v35, v19, v31
	v_cndmask_b32_e64 v19, v31, v19, s[40:41]
	v_and_b32_e32 v23, 0xffff0000, v27
	v_fma_f32 v23, v43, v23, v19
	v_fma_f32 v28, -v25, v26, 1.0
	v_cndmask_b32_e64 v19, v19, v23, s[42:43]
	v_fmac_f32_e32 v26, v28, v26
	v_div_scale_f32 v28, vcc, v22, v24, v22
	v_mul_f32_e32 v23, 0xbfb8aa3b, v19
	v_mul_f32_e32 v29, v28, v26
	v_exp_f32_e32 v23, v23
	v_fma_f32 v30, -v25, v29, v28
	v_fmac_f32_e32 v29, v30, v26
	v_fma_f32 v25, -v25, v29, v28
	v_div_fmas_f32 v25, v25, v26, v29
	v_add_f32_e32 v23, 1.0, v23
	v_div_fixup_f32 v22, v25, v24, v22
	v_div_scale_f32 v24, s[0:1], v23, v23, v19
	v_rcp_f32_e32 v25, v24
	v_cvt_pk_bf16_f32 v18, v21, v18
	v_lshlrev_b64 v[20:21], 11, v[88:89]
	v_lshl_add_u64 v[20:21], s[34:35], 0, v[20:21]
	v_fma_f32 v26, -v24, v25, 1.0
	v_fmac_f32_e32 v25, v26, v25
	v_div_scale_f32 v26, vcc, v19, v23, v19
	v_mul_f32_e32 v27, v26, v25
	v_fma_f32 v28, -v24, v27, v26
	v_fmac_f32_e32 v27, v28, v25
	v_fma_f32 v24, -v24, v27, v26
	v_div_fmas_f32 v24, v24, v25, v27
	v_div_fixup_f32 v19, v24, v23, v19
	v_lshl_add_u64 v[20:21], v[86:87], 1, v[20:21]
	v_cvt_pk_bf16_f32 v19, v22, v19
	global_store_dwordx4 v[20:21], v[16:19], off
	v_mad_u64_u32 v[28:29], s[0:1], v81, s79, v[2:3]
	ds_read_b128 v[32:35], v28 offset:40448
	ds_read_b128 v[16:19], v28 offset:40464
	ds_read_b128 v[36:39], v28 offset:32768
	ds_read_b128 v[20:23], v28 offset:32784
	ds_read_b128 v[40:43], v28 offset:35328
	ds_read_b128 v[24:27], v28 offset:35344
	ds_read_b128 v[44:47], v28 offset:37888
	ds_read_b128 v[28:31], v28 offset:37904
	v_add_u32_e32 v2, 0xa000, v2
	s_waitcnt lgkmcnt(3)
	v_fma_f32 v32, v40, v48, v32
	s_waitcnt vmcnt(4)
	v_lshlrev_b32_e32 v40, 16, v8
	v_fma_f32 v36, v36, v40, v32
	v_cndmask_b32_e64 v32, v32, v36, s[36:37]
	v_lshlrev_b32_e32 v36, 16, v12
	s_waitcnt lgkmcnt(1)
	v_fma_f32 v36, v44, v36, v32
	v_cndmask_b32_e64 v32, v32, v36, s[38:39]
	v_mul_f32_e32 v36, 0xbfb8aa3b, v32
	v_exp_f32_e32 v36, v36
	v_fma_f32 v4, v41, v4, v33
	v_and_b32_e32 v8, 0xffff0000, v8
	v_fma_f32 v8, v37, v8, v4
	v_cndmask_b32_e64 v4, v4, v8, s[36:37]
	v_and_b32_e32 v8, 0xffff0000, v12
	v_add_f32_e32 v36, 1.0, v36
	v_fma_f32 v8, v45, v8, v4
	v_div_scale_f32 v40, s[0:1], v36, v36, v32
	v_cndmask_b32_e64 v4, v4, v8, s[38:39]
	v_rcp_f32_e32 v44, v40
	v_mul_f32_e32 v8, 0xbfb8aa3b, v4
	v_exp_f32_e32 v8, v8
	v_fma_f32 v48, -v40, v44, 1.0
	v_fmac_f32_e32 v44, v48, v44
	v_div_scale_f32 v48, vcc, v32, v36, v32
	v_add_f32_e32 v8, 1.0, v8
	v_mul_f32_e32 v49, v48, v44
	v_div_scale_f32 v12, s[0:1], v8, v8, v4
	v_fma_f32 v50, -v40, v49, v48
	v_rcp_f32_e32 v33, v12
	v_fmac_f32_e32 v49, v50, v44
	v_fma_f32 v40, -v40, v49, v48
	v_div_fmas_f32 v40, v40, v44, v49
	v_div_fixup_f32 v32, v40, v36, v32
	v_fma_f32 v36, -v12, v33, 1.0
	v_fmac_f32_e32 v33, v36, v33
	v_div_scale_f32 v36, vcc, v4, v8, v4
	v_mul_f32_e32 v37, v36, v33
	v_fma_f32 v40, -v12, v37, v36
	v_fmac_f32_e32 v37, v40, v33
	v_fma_f32 v12, -v12, v37, v36
	v_div_fmas_f32 v12, v12, v33, v37
	v_div_fixup_f32 v4, v12, v8, v4
	v_lshlrev_b32_e32 v8, 16, v5
	v_fma_f32 v8, v42, v8, v34
	v_lshlrev_b32_e32 v12, 16, v9
	v_fma_f32 v12, v38, v12, v8
	v_cndmask_b32_e64 v8, v8, v12, s[36:37]
	v_lshlrev_b32_e32 v12, 16, v13
	v_fma_f32 v12, v46, v12, v8
	v_cndmask_b32_e64 v8, v8, v12, s[38:39]
	v_mul_f32_e32 v12, 0xbfb8aa3b, v8
	v_exp_f32_e32 v12, v12
	v_and_b32_e32 v5, 0xffff0000, v5
	v_fmac_f32_e32 v35, v43, v5
	v_and_b32_e32 v5, 0xffff0000, v9
	v_add_f32_e32 v12, 1.0, v12
	v_div_scale_f32 v33, s[0:1], v12, v12, v8
	v_rcp_f32_e32 v34, v33
	v_fma_f32 v5, v39, v5, v35
	v_cndmask_b32_e64 v5, v35, v5, s[36:37]
	v_and_b32_e32 v9, 0xffff0000, v13
	v_fma_f32 v9, v47, v9, v5
	v_fma_f32 v36, -v33, v34, 1.0
	v_cndmask_b32_e64 v5, v5, v9, s[38:39]
	v_fmac_f32_e32 v34, v36, v34
	v_div_scale_f32 v36, vcc, v8, v12, v8
	v_mul_f32_e32 v9, 0xbfb8aa3b, v5
	v_mul_f32_e32 v37, v36, v34
	v_exp_f32_e32 v9, v9
	v_fma_f32 v38, -v33, v37, v36
	v_fmac_f32_e32 v37, v38, v34
	v_fma_f32 v33, -v33, v37, v36
	v_div_fmas_f32 v33, v33, v34, v37
	v_add_f32_e32 v9, 1.0, v9
	v_div_fixup_f32 v8, v33, v12, v8
	v_div_scale_f32 v12, s[0:1], v9, v9, v5
	v_rcp_f32_e32 v13, v12
	v_cvt_pk_bf16_f32 v4, v32, v4
	s_nop 0
	v_fma_f32 v33, -v12, v13, 1.0
	v_fmac_f32_e32 v13, v33, v13
	v_div_scale_f32 v33, vcc, v5, v9, v5
	v_mul_f32_e32 v34, v33, v13
	v_fma_f32 v35, -v12, v34, v33
	v_fmac_f32_e32 v34, v35, v13
	v_fma_f32 v12, -v12, v34, v33
	v_div_fmas_f32 v12, v12, v13, v34
	v_div_fixup_f32 v5, v12, v9, v5
	v_lshlrev_b32_e32 v9, 16, v6
	v_fma_f32 v9, v24, v9, v16
	v_lshlrev_b32_e32 v12, 16, v10
	v_fma_f32 v12, v20, v12, v9
	v_cndmask_b32_e64 v9, v9, v12, s[36:37]
	v_lshlrev_b32_e32 v12, 16, v14
	s_waitcnt lgkmcnt(0)
; DI float bf2f(bf16_t v) { return __uint_as_float(((unsigned)v) << 16); }
; DI float silu(float x) { return x / (1.f + __expf(-x)); }
; DI void ssmconv_item(const Params& p, int layer, int it, const float* w, const float* bb) {
;     ...
;         for (int j = 0; j < 5; ++j) { const int i = tid + 256 * (j0 + j), rl = i / 80, c = (i - rl * 80) * 8, t = t0 + rl; const size_t r = r0 + rl;
;             const bf16_t* src = PROJ + r * INP + O_XBC + c;
;             xc[j] = ld8(src); xp[j] = xc[j]; xn[j] = xc[j];
;             if (t > 0) xp[j] = ld8(src - INP);
;             if (t < L - 1) xn[j] = ld8(src + INP); }
;     ...
;             for (int e = 0; e < 8; ++e) { float v = bv[e] + w1v[e] * bf2f((bf16_t)xc[j][e]);
;                 if (hp) v += w0v[e] * bf2f((bf16_t)xp[j][e]);
;                 if (hn) v += w2v[e] * bf2f((bf16_t)xn[j][e]);
;                 o[e] = silu(v); }
;             *(bf16x8*)(UZ + r * 1024 + c) = pack8(o[0], o[1], o[2], o[3], o[4], o[5], o[6], o[7]); }
	v_fma_f32 v12, v28, v12, v9
	v_cndmask_b32_e64 v9, v9, v12, s[38:39]
	v_mul_f32_e32 v12, 0xbfb8aa3b, v9
	v_exp_f32_e32 v12, v12
	v_and_b32_e32 v6, 0xffff0000, v6
	v_fma_f32 v6, v25, v6, v17
	v_and_b32_e32 v10, 0xffff0000, v10
	v_add_f32_e32 v12, 1.0, v12
	v_div_scale_f32 v13, s[0:1], v12, v12, v9
	v_rcp_f32_e32 v16, v13
	v_fma_f32 v10, v21, v10, v6
	v_cndmask_b32_e64 v6, v6, v10, s[36:37]
	v_and_b32_e32 v10, 0xffff0000, v14
	v_fma_f32 v10, v29, v10, v6
	v_fma_f32 v20, -v13, v16, 1.0
	v_cndmask_b32_e64 v6, v6, v10, s[38:39]
	v_fmac_f32_e32 v16, v20, v16
	v_div_scale_f32 v20, vcc, v9, v12, v9
	v_mul_f32_e32 v10, 0xbfb8aa3b, v6
	v_mul_f32_e32 v24, v20, v16
	v_exp_f32_e32 v10, v10
	v_fma_f32 v28, -v13, v24, v20
	v_fmac_f32_e32 v24, v28, v16
	v_fma_f32 v13, -v13, v24, v20
	v_div_fmas_f32 v13, v13, v16, v24
	v_add_f32_e32 v10, 1.0, v10
	v_div_fixup_f32 v9, v13, v12, v9
	v_div_scale_f32 v12, s[0:1], v10, v10, v6
	v_rcp_f32_e32 v13, v12
	v_cvt_pk_bf16_f32 v5, v8, v5
	s_nop 0
	v_fma_f32 v14, -v12, v13, 1.0
	v_fmac_f32_e32 v13, v14, v13
	v_div_scale_f32 v14, vcc, v6, v10, v6
	v_mul_f32_e32 v16, v14, v13
	v_fma_f32 v17, -v12, v16, v14
	v_fmac_f32_e32 v16, v17, v13
	v_fma_f32 v12, -v12, v16, v14
	v_div_fmas_f32 v12, v12, v13, v16
	v_div_fixup_f32 v6, v12, v10, v6
	v_lshlrev_b32_e32 v10, 16, v7
	v_fma_f32 v10, v26, v10, v18
	v_lshlrev_b32_e32 v12, 16, v11
	v_fma_f32 v12, v22, v12, v10
	v_cndmask_b32_e64 v10, v10, v12, s[36:37]
	v_lshlrev_b32_e32 v12, 16, v15
	v_fma_f32 v12, v30, v12, v10
	v_cndmask_b32_e64 v10, v10, v12, s[38:39]
	v_mul_f32_e32 v12, 0xbfb8aa3b, v10
	v_exp_f32_e32 v12, v12
	v_and_b32_e32 v7, 0xffff0000, v7
	v_fmac_f32_e32 v19, v27, v7
	v_and_b32_e32 v7, 0xffff0000, v11
	v_add_f32_e32 v12, 1.0, v12
	v_div_scale_f32 v13, s[0:1], v12, v12, v10
	v_rcp_f32_e32 v14, v13
	v_fma_f32 v7, v23, v7, v19
	v_cndmask_b32_e64 v7, v19, v7, s[36:37]
	v_and_b32_e32 v11, 0xffff0000, v15
	v_fma_f32 v11, v31, v11, v7
	v_fma_f32 v16, -v13, v14, 1.0
	v_cndmask_b32_e64 v7, v7, v11, s[38:39]
	v_fmac_f32_e32 v14, v16, v14
	v_div_scale_f32 v16, vcc, v10, v12, v10
	v_mul_f32_e32 v11, 0xbfb8aa3b, v7
	v_mul_f32_e32 v17, v16, v14
	v_exp_f32_e32 v11, v11
	v_fma_f32 v18, -v13, v17, v16
	v_fmac_f32_e32 v17, v18, v14
	v_fma_f32 v13, -v13, v17, v16
	v_div_fmas_f32 v13, v13, v14, v17
	v_add_f32_e32 v11, 1.0, v11
	v_div_fixup_f32 v10, v13, v12, v10
	v_div_scale_f32 v12, s[0:1], v11, v11, v7
	v_rcp_f32_e32 v13, v12
	v_cvt_pk_bf16_f32 v6, v9, v6
	v_lshlrev_b64 v[8:9], 11, v[84:85]
	v_lshl_add_u64 v[8:9], s[34:35], 0, v[8:9]
	v_fma_f32 v14, -v12, v13, 1.0
	v_fmac_f32_e32 v13, v14, v13
	v_div_scale_f32 v14, vcc, v7, v11, v7
	v_mul_f32_e32 v15, v14, v13
	v_fma_f32 v16, -v12, v15, v14
	v_fmac_f32_e32 v15, v16, v13
	v_fma_f32 v12, -v12, v15, v14
	v_div_fmas_f32 v12, v12, v13, v15
	v_add_co_u32_e32 v1, vcc, 5, v1
	v_div_fixup_f32 v7, v12, v11, v7
	v_lshl_add_u64 v[8:9], v[82:83], 1, v[8:9]
	s_andn2_b64 vcc, exec, vcc
	v_cvt_pk_bf16_f32 v7, v10, v7
	global_store_dwordx4 v[8:9], v[4:7], off
	s_cbranch_vccnz .LBB0_1529
.LBB0_1509:
	s_nop 0
	v_add_u32_e32 v6, s76, v0
	v_mul_hi_i32 v4, v6, s77
	v_lshrrev_b32_e32 v5, 31, v4
	v_ashrrev_i32_e32 v4, 5, v4
	v_add_u32_e32 v66, v4, v5
	v_mad_u64_u32 v[98:99], s[0:1], v66, s90, v[80:81]
	v_add_u32_e32 v100, s72, v66
	v_mov_b64_e32 v[4:5], s[2:3]
	v_mad_i64_i32 v[4:5], s[0:1], v100, s89, v[4:5]
	v_ashrrev_i32_e32 v99, 31, v98
	v_lshl_add_u64 v[4:5], v[98:99], 1, v[4:5]
	global_load_dwordx4 v[52:55], v[4:5], off offset:1600
	v_add_u32_e32 v7, s95, v66
	v_cmp_lt_i32_e64 s[0:1], 0, v7
	s_and_saveexec_b64 s[10:11], s[0:1]
	s_cbranch_execz .LBB0_1511
	global_load_dwordx4 v[56:59], v[4:5], off offset:-3008
.LBB0_1511:
	s_or_b64 exec, exec, s[10:11]
	v_cmp_gt_i32_e64 s[54:55], s94, v7
	s_and_saveexec_b64 s[36:37], s[54:55]
	s_cbranch_execz .LBB0_1513
	v_lshl_add_u64 v[4:5], v[4:5], 0, s[16:17]
	v_add_co_u32_e32 v4, vcc, 0x1000, v4
	s_nop 1
	v_addc_co_u32_e32 v5, vcc, 0, v5, vcc
	global_load_dwordx4 v[60:63], v[4:5], off offset:512
; DI void ssmconv_item(const Params& p, int layer, int it, const float* w, const float* bb) {
;     ...
;         for (int j = 0; j < 5; ++j) { const int i = tid + 256 * (j0 + j), rl = i / 80, c = (i - rl * 80) * 8, t = t0 + rl; const size_t r = r0 + rl;
;             const bf16_t* src = PROJ + r * INP + O_XBC + c;
;             xc[j] = ld8(src); xp[j] = xc[j]; xn[j] = xc[j];
;             if (t > 0) xp[j] = ld8(src - INP);
;             if (t < L - 1) xn[j] = ld8(src + INP); }
.LBB0_1513:
	s_or_b64 exec, exec, s[36:37]
	v_add_u32_e32 v4, 0x100, v6
	v_mul_hi_i32 v4, v4, s77
	v_lshrrev_b32_e32 v5, 31, v4
	v_ashrrev_i32_e32 v4, 5, v4
	v_add_u32_e32 v104, v4, v5
	v_mul_lo_u32 v4, v104, s90
	v_add3_u32 v94, v80, v4, s78
	v_add_u32_e32 v96, s72, v104
	v_mov_b64_e32 v[4:5], s[2:3]
	v_mad_i64_i32 v[4:5], s[10:11], v96, s89, v[4:5]
	v_ashrrev_i32_e32 v95, 31, v94
	v_lshl_add_u64 v[4:5], v[94:95], 1, v[4:5]
	global_load_dwordx4 v[40:43], v[4:5], off offset:1600
	v_add_u32_e32 v7, s95, v104
	v_cmp_lt_i32_e64 s[48:49], 0, v7
	s_and_saveexec_b64 s[10:11], s[48:49]
	s_cbranch_execz .LBB0_1515
	global_load_dwordx4 v[44:47], v[4:5], off offset:-3008
.LBB0_1515:
	s_or_b64 exec, exec, s[10:11]
	v_cmp_gt_i32_e64 s[50:51], s94, v7
	s_and_saveexec_b64 s[36:37], s[50:51]
	s_cbranch_execz .LBB0_1517
	v_lshl_add_u64 v[4:5], v[4:5], 0, s[16:17]
	v_add_co_u32_e32 v4, vcc, 0x1000, v4
	s_nop 1
	v_addc_co_u32_e32 v5, vcc, 0, v5, vcc
	global_load_dwordx4 v[48:51], v[4:5], off offset:512
.LBB0_1517:
	s_or_b64 exec, exec, s[36:37]
	v_add_u32_e32 v4, 0x200, v6
	v_mul_hi_i32 v4, v4, s77
	v_lshrrev_b32_e32 v5, 31, v4
	v_ashrrev_i32_e32 v4, 5, v4
	v_add_u32_e32 v103, v4, v5
	v_mul_lo_u32 v4, v103, s90
	v_add3_u32 v90, v80, v4, s82
	v_add_u32_e32 v92, s72, v103
	v_mov_b64_e32 v[4:5], s[2:3]
	v_mad_i64_i32 v[4:5], s[10:11], v92, s89, v[4:5]
	v_ashrrev_i32_e32 v91, 31, v90
	v_lshl_add_u64 v[4:5], v[90:91], 1, v[4:5]
	global_load_dwordx4 v[28:31], v[4:5], off offset:1600
	v_add_u32_e32 v7, s95, v103
	v_cmp_lt_i32_e64 s[44:45], 0, v7
	s_and_saveexec_b64 s[10:11], s[44:45]
	s_cbranch_execz .LBB0_1519
	global_load_dwordx4 v[32:35], v[4:5], off offset:-3008
.LBB0_1519:
	s_or_b64 exec, exec, s[10:11]
	v_cmp_gt_i32_e64 s[46:47], s94, v7
	s_and_saveexec_b64 s[36:37], s[46:47]
	s_cbranch_execz .LBB0_1521
	v_lshl_add_u64 v[4:5], v[4:5], 0, s[16:17]
	v_add_co_u32_e32 v4, vcc, 0x1000, v4
	s_nop 1
	v_addc_co_u32_e32 v5, vcc, 0, v5, vcc
	global_load_dwordx4 v[36:39], v[4:5], off offset:512
.LBB0_1521:
	s_or_b64 exec, exec, s[36:37]
	v_add_u32_e32 v4, 0x300, v6
	v_mul_hi_i32 v4, v4, s77
	v_lshrrev_b32_e32 v5, 31, v4
	v_ashrrev_i32_e32 v4, 5, v4
	v_add_u32_e32 v102, v4, v5
	v_mul_lo_u32 v4, v102, s90
	s_movk_i32 s10, 0x1800
	v_add3_u32 v86, v80, v4, s10
	v_add_u32_e32 v88, s72, v102
	v_mov_b64_e32 v[4:5], s[2:3]
	v_mad_i64_i32 v[4:5], s[10:11], v88, s89, v[4:5]
	v_ashrrev_i32_e32 v87, 31, v86
	v_lshl_add_u64 v[4:5], v[86:87], 1, v[4:5]
	global_load_dwordx4 v[16:19], v[4:5], off offset:1600
	v_add_u32_e32 v7, s95, v102
	v_cmp_lt_i32_e64 s[40:41], 0, v7
	s_and_saveexec_b64 s[10:11], s[40:41]
	s_cbranch_execz .LBB0_1523
	global_load_dwordx4 v[20:23], v[4:5], off offset:-3008
.LBB0_1523:
	s_or_b64 exec, exec, s[10:11]
	v_cmp_gt_i32_e64 s[42:43], s94, v7
	s_and_saveexec_b64 s[36:37], s[42:43]
	s_cbranch_execz .LBB0_1525
	v_lshl_add_u64 v[4:5], v[4:5], 0, s[16:17]
	v_add_co_u32_e32 v4, vcc, 0x1000, v4
	s_nop 1
	v_addc_co_u32_e32 v5, vcc, 0, v5, vcc
	global_load_dwordx4 v[24:27], v[4:5], off offset:512
.LBB0_1525:
	s_or_b64 exec, exec, s[36:37]
	v_add_u32_e32 v4, 0x400, v6
	v_mul_hi_i32 v4, v4, s77
	v_lshrrev_b32_e32 v5, 31, v4
	v_ashrrev_i32_e32 v4, 5, v4
	v_add_u32_e32 v81, v4, v5
	v_mul_lo_u32 v4, v81, s90
	v_add3_u32 v82, v80, v4, s81
	v_add_u32_e32 v84, s72, v81
	v_mov_b64_e32 v[4:5], s[2:3]
	v_mad_i64_i32 v[4:5], s[10:11], v84, s89, v[4:5]
	v_ashrrev_i32_e32 v83, 31, v82
	v_lshl_add_u64 v[64:65], v[82:83], 1, v[4:5]
	global_load_dwordx4 v[4:7], v[64:65], off offset:1600
	v_add_u32_e32 v12, s95, v81
	v_cmp_lt_i32_e64 s[36:37], 0, v12
	s_and_saveexec_b64 s[10:11], s[36:37]
	s_cbranch_execz .LBB0_1527
	global_load_dwordx4 v[8:11], v[64:65], off offset:-3008
.LBB0_1527:
	s_or_b64 exec, exec, s[10:11]
	v_cmp_gt_i32_e64 s[38:39], s94, v12
	s_and_saveexec_b64 s[10:11], s[38:39]
	s_cbranch_execz .LBB0_1508
	v_lshl_add_u64 v[12:13], v[64:65], 0, s[16:17]
	v_add_co_u32_e32 v12, vcc, 0x1000, v12
	s_nop 1
	v_addc_co_u32_e32 v13, vcc, 0, v13, vcc
	global_load_dwordx4 v[12:15], v[12:13], off offset:512
	s_branch .LBB0_1508
